# GEMM K-loops slimmed: vmcnt+lgkmcnt waits merged, redundant post-barrier lgkmcnt wait and mid-segment setprio pair removed, B-fragment LDS reads from one base VGPR with immediate offsets
# speedup vs baseline: 1.0119x; 1.0026x over previous
; #define PG8_STAGE(bufoff, gbase, voff) do { _Pragma("unroll") for (int _i = 0; _i < 2; ++_i) \
;         __builtin_amdgcn_global_load_lds((const unsigned*)((const char*)(gbase) + (voff)[_i]), (LAS unsigned*)(lds + (bufoff) + ldsw + _i * 8192), 16, 0, 0); } while (0)
; #define PG8_LDA(dst, b, h) do { _Pragma("unroll") for (int m = 0; m < 4; ++m) _Pragma("unroll") for (int k = 0; k < 2; ++k) dst[m][k] = *(const LAS bf16x8*)(lds + PG8_SA(b, h) + aoff + m * 2048 + k * 1024); } while (0)
; #define PG8_LDB(dst, b, h) do { _Pragma("unroll") for (int n = 0; n < 2; ++n) _Pragma("unroll") for (int k = 0; k < 2; ++k) dst[n][k] = *(const LAS bf16x8*)(lds + PG8_SB(b, h) + boff + n * 2048 + k * 1024); } while (0)
; #define PG8_MMA(ai, bj, At, Bt) do { __builtin_amdgcn_s_setprio(1); _Pragma("unroll") for (int m = 0; m < 4; ++m) _Pragma("unroll") for (int n = 0; n < 2; ++n) _Pragma("unroll") for (int k = 0; k < 2; ++k) \
;         acc[ai][bj][m][n] = __builtin_amdgcn_mfma_f32_16x16x32_bf16(Bt[n][k], At[m][k], acc[ai][bj][m][n], 0, 0, 0); __builtin_amdgcn_s_setprio(0); } while (0)
; #define PG8_WAIT_V(n) asm volatile("s_waitcnt vmcnt(" #n ")" ::: "memory")
; #define PG8_WAIT_L(n) asm volatile("s_waitcnt lgkmcnt(" #n ")" ::: "memory")
; #define PG8_BAR __builtin_amdgcn_s_barrier()
; template <class Epi, class Sched>
; DI void gemm_phase(LAS unsigned char* lds, const Sched& S, const Epi& E) {
;     ...
;         for (int t = 0; t < nt; t += 2) {
;             const bool last = (t == nt - 2);
;             const char* a1 = cA + (size_t)(t + 1) * kstep;
;             const char* a2 = last ? nA : cA + (size_t)(t + 2) * kstep; const char* b2 = last ? nB : cB + (size_t)(t + 2) * kstep;
;             const char* a3 = a2 + kstep; const char* b3 = b2 + kstep;
;             if constexpr (Epi::HOOK) { if (cur.ks < 0 && (t == 16 || t == 32)) E.hook(acc, cur, t >> 4, wr, wc, fr, fq); }
;             PG8_LDB(B0, 0, 0); PG8_LDB(B1, 0, 1); PG8_SCHED; PG8_LDA(At, 0, 0); PG8_STAGE(PG8_SA(1, 1), a1 + hstepA, voffA);
;             PG8_WAIT_V(8); PG8_WAIT_L(0); PG8_BAR; PG8_MMA(0, 0, At, B0); PG8_MMA(0, 1, At, B1); PG8_BAR; PG8_SCHED;
;             PG8_LDA(At, 0, 1); PG8_STAGE(PG8_SB(0, 0), b2, voffB); PG8_STAGE(PG8_SB(0, 1), b2 + hstepB, voffB); PG8_STAGE(PG8_SA(0, 0), a2, voffA);
;             PG8_WAIT_V(8); PG8_WAIT_L(0); PG8_BAR; PG8_MMA(1, 0, At, B0); PG8_MMA(1, 1, At, B1); PG8_BAR; PG8_SCHED;
.LBB0_156:
	v_add_u32_e32 v216, 0x10000, v145
	s_add_i32 s82, s8, 2
	s_add_u32 s9, s4, 0xfff80080
	s_addc_u32 s40, s5, -1
	s_add_i32 s83, 0, 0x10000
	s_cmp_eq_u32 s79, s8
	s_cselect_b32 s41, s42, s40
	s_cselect_b32 s40, s43, s9
	s_cselect_b32 s9, s53, s81
	s_cselect_b32 s8, s57, s80
	s_add_i32 s85, 0, 0x14000
	ds_read_b128 v[52:55], v216
	ds_read_b128 v[156:159], v216 offset:1024
	ds_read_b128 v[160:163], v216 offset:2048
	ds_read_b128 v[168:171], v216 offset:3072
	ds_read_b128 v[172:175], v216 offset:16384
	ds_read_b128 v[176:179], v216 offset:17408
	ds_read_b128 v[180:183], v216 offset:18432
	ds_read_b128 v[184:187], v216 offset:19456
	s_add_i32 m0, s62, 0xc000
	ds_read_b128 v[188:191], v166
	ds_read_b128 v[192:195], v166 offset:1024
	ds_read_b128 v[204:207], v166 offset:2048
	ds_read_b128 v[208:211], v166 offset:3072
	ds_read_b128 v[212:215], v166 offset:4096
	ds_read_b128 v[230:233], v166 offset:5120
	ds_read_b128 v[234:237], v166 offset:6144
	global_load_lds_dwordx4 v154, s[4:5]
	s_add_i32 m0, s62, 0xe000
	ds_read_b128 v[238:241], v166 offset:7168
	global_load_lds_dwordx4 v152, s[4:5]
	s_waitcnt vmcnt(8) lgkmcnt(0)
	s_barrier
	s_setprio 1
	v_mfma_f32_16x16x32_bf16 v[132:135], v[52:55], v[188:191], v[132:135]
	v_mfma_f32_16x16x32_bf16 v[128:131], v[160:163], v[188:191], v[128:131]
	v_mfma_f32_16x16x32_bf16 v[116:119], v[52:55], v[204:207], v[116:119]
	v_mfma_f32_16x16x32_bf16 v[112:115], v[160:163], v[204:207], v[112:115]
	v_mfma_f32_16x16x32_bf16 v[100:103], v[52:55], v[212:215], v[100:103]
	v_mfma_f32_16x16x32_bf16 v[96:99], v[160:163], v[212:215], v[96:99]
	v_mfma_f32_16x16x32_bf16 v[84:87], v[52:55], v[234:237], v[84:87]
	v_mfma_f32_16x16x32_bf16 v[80:83], v[160:163], v[234:237], v[80:83]
	v_mfma_f32_16x16x32_bf16 v[132:135], v[156:159], v[192:195], v[132:135]
	v_mfma_f32_16x16x32_bf16 v[128:131], v[168:171], v[192:195], v[128:131]
	v_mfma_f32_16x16x32_bf16 v[116:119], v[156:159], v[208:211], v[116:119]
	v_mfma_f32_16x16x32_bf16 v[112:115], v[168:171], v[208:211], v[112:115]
	v_mfma_f32_16x16x32_bf16 v[100:103], v[156:159], v[230:233], v[100:103]
	v_mfma_f32_16x16x32_bf16 v[96:99], v[168:171], v[230:233], v[96:99]
	v_mfma_f32_16x16x32_bf16 v[84:87], v[156:159], v[238:241], v[84:87]
	v_mfma_f32_16x16x32_bf16 v[80:83], v[168:171], v[238:241], v[80:83]
	v_mfma_f32_16x16x32_bf16 v[124:127], v[172:175], v[188:191], v[124:127]
	v_mfma_f32_16x16x32_bf16 v[120:123], v[180:183], v[188:191], v[120:123]
	v_mfma_f32_16x16x32_bf16 v[108:111], v[172:175], v[204:207], v[108:111]
	v_mfma_f32_16x16x32_bf16 v[104:107], v[180:183], v[204:207], v[104:107]
	v_mfma_f32_16x16x32_bf16 v[92:95], v[172:175], v[212:215], v[92:95]
	v_mfma_f32_16x16x32_bf16 v[88:91], v[180:183], v[212:215], v[88:91]
	v_mfma_f32_16x16x32_bf16 v[76:79], v[172:175], v[234:237], v[76:79]
	v_mfma_f32_16x16x32_bf16 v[72:75], v[180:183], v[234:237], v[72:75]
	v_mfma_f32_16x16x32_bf16 v[124:127], v[176:179], v[192:195], v[124:127]
	v_mfma_f32_16x16x32_bf16 v[120:123], v[184:187], v[192:195], v[120:123]
	v_mfma_f32_16x16x32_bf16 v[108:111], v[176:179], v[208:211], v[108:111]
	v_mfma_f32_16x16x32_bf16 v[104:107], v[184:187], v[208:211], v[104:107]
	v_mfma_f32_16x16x32_bf16 v[92:95], v[176:179], v[230:233], v[92:95]
	v_mfma_f32_16x16x32_bf16 v[88:91], v[184:187], v[230:233], v[88:91]
	v_mfma_f32_16x16x32_bf16 v[76:79], v[176:179], v[238:241], v[76:79]
	v_mfma_f32_16x16x32_bf16 v[72:75], v[184:187], v[238:241], v[72:75]
	s_setprio 0
	s_barrier
	s_add_i32 s83, s83, s27
	s_mov_b32 m0, s83
	ds_read_b128 v[188:191], v166 offset:16384
	ds_read_b128 v[192:195], v166 offset:17408
	ds_read_b128 v[204:207], v166 offset:18432
	ds_read_b128 v[208:211], v166 offset:19456
	global_load_lds_dwordx4 v138, s[8:9]
	s_add_i32 m0, s83, 0x2000
	s_add_u32 s86, s8, 0x80000
	s_addc_u32 s87, s9, 0
	s_add_i32 s83, s85, s27
	global_load_lds_dwordx4 v142, s[8:9]
	s_mov_b32 m0, s83
	ds_read_b128 v[238:241], v166 offset:23552
	global_load_lds_dwordx4 v138, s[86:87]
	s_add_i32 m0, s83, 0x2000
	ds_read_b128 v[234:237], v166 offset:22528
	global_load_lds_dwordx4 v142, s[86:87]
	s_add_u32 s98, s40, 0x80
	s_addc_u32 s99, s41, 0
	s_mov_b32 m0, s62
	ds_read_b128 v[230:233], v166 offset:21504
	global_load_lds_dwordx4 v136, s[40:41]
	s_mov_b32 m0, s63
	ds_read_b128 v[212:215], v166 offset:20480
	global_load_lds_dwordx4 v140, s[40:41]
	s_waitcnt vmcnt(8) lgkmcnt(0)
	s_barrier
	s_setprio 1
	v_mfma_f32_16x16x32_bf16 v[68:71], v[52:55], v[188:191], v[68:71]
	v_mfma_f32_16x16x32_bf16 v[64:67], v[160:163], v[188:191], v[64:67]
	v_mfma_f32_16x16x32_bf16 v[48:51], v[52:55], v[204:207], v[48:51]
	v_mfma_f32_16x16x32_bf16 v[44:47], v[160:163], v[204:207], v[44:47]
	v_mfma_f32_16x16x32_bf16 v[32:35], v[52:55], v[212:215], v[32:35]
	v_mfma_f32_16x16x32_bf16 v[28:31], v[160:163], v[212:215], v[28:31]
	v_mfma_f32_16x16x32_bf16 v[16:19], v[52:55], v[234:237], v[16:19]
	v_mfma_f32_16x16x32_bf16 v[12:15], v[160:163], v[234:237], v[12:15]
	v_mfma_f32_16x16x32_bf16 v[68:71], v[156:159], v[192:195], v[68:71]
	v_mfma_f32_16x16x32_bf16 v[64:67], v[168:171], v[192:195], v[64:67]
	v_mfma_f32_16x16x32_bf16 v[48:51], v[156:159], v[208:211], v[48:51]
	v_mfma_f32_16x16x32_bf16 v[44:47], v[168:171], v[208:211], v[44:47]
	v_mfma_f32_16x16x32_bf16 v[32:35], v[156:159], v[230:233], v[32:35]
	v_mfma_f32_16x16x32_bf16 v[28:31], v[168:171], v[230:233], v[28:31]
	v_mfma_f32_16x16x32_bf16 v[16:19], v[156:159], v[238:241], v[16:19]
	v_mfma_f32_16x16x32_bf16 v[12:15], v[168:171], v[238:241], v[12:15]
	v_mfma_f32_16x16x32_bf16 v[56:59], v[180:183], v[188:191], v[56:59]
	v_mfma_f32_16x16x32_bf16 v[40:43], v[172:175], v[204:207], v[40:43]
	v_mfma_f32_16x16x32_bf16 v[36:39], v[180:183], v[204:207], v[36:39]
	v_mfma_f32_16x16x32_bf16 v[24:27], v[172:175], v[212:215], v[24:27]
	v_mfma_f32_16x16x32_bf16 v[20:23], v[180:183], v[212:215], v[20:23]
	v_mfma_f32_16x16x32_bf16 v[8:11], v[172:175], v[234:237], v[8:11]
	v_mfma_f32_16x16x32_bf16 v[4:7], v[180:183], v[234:237], v[4:7]
	v_mfma_f32_16x16x32_bf16 v[52:55], v[172:175], v[188:191], v[60:63]
	v_mfma_f32_16x16x32_bf16 v[56:59], v[184:187], v[192:195], v[56:59]
	v_mfma_f32_16x16x32_bf16 v[40:43], v[176:179], v[208:211], v[40:43]
	v_mfma_f32_16x16x32_bf16 v[36:39], v[184:187], v[208:211], v[36:39]
	v_mfma_f32_16x16x32_bf16 v[24:27], v[176:179], v[230:233], v[24:27]
	v_mfma_f32_16x16x32_bf16 v[20:23], v[184:187], v[230:233], v[20:23]
	v_mfma_f32_16x16x32_bf16 v[8:11], v[176:179], v[238:241], v[8:11]
	v_mfma_f32_16x16x32_bf16 v[4:7], v[184:187], v[238:241], v[4:7]
	v_mfma_f32_16x16x32_bf16 v[52:55], v[176:179], v[192:195], v[52:55]
	s_setprio 0
	s_barrier
; #define PG8_STAGE(bufoff, gbase, voff) do { _Pragma("unroll") for (int _i = 0; _i < 2; ++_i) \
;         __builtin_amdgcn_global_load_lds((const unsigned*)((const char*)(gbase) + (voff)[_i]), (LAS unsigned*)(lds + (bufoff) + ldsw + _i * 8192), 16, 0, 0); } while (0)
; #define PG8_LDA(dst, b, h) do { _Pragma("unroll") for (int m = 0; m < 4; ++m) _Pragma("unroll") for (int k = 0; k < 2; ++k) dst[m][k] = *(const LAS bf16x8*)(lds + PG8_SA(b, h) + aoff + m * 2048 + k * 1024); } while (0)
; #define PG8_LDB(dst, b, h) do { _Pragma("unroll") for (int n = 0; n < 2; ++n) _Pragma("unroll") for (int k = 0; k < 2; ++k) dst[n][k] = *(const LAS bf16x8*)(lds + PG8_SB(b, h) + boff + n * 2048 + k * 1024); } while (0)
; #define PG8_MMA(ai, bj, At, Bt) do { __builtin_amdgcn_s_setprio(1); _Pragma("unroll") for (int m = 0; m < 4; ++m) _Pragma("unroll") for (int n = 0; n < 2; ++n) _Pragma("unroll") for (int k = 0; k < 2; ++k) \
;         acc[ai][bj][m][n] = __builtin_amdgcn_mfma_f32_16x16x32_bf16(Bt[n][k], At[m][k], acc[ai][bj][m][n], 0, 0, 0); __builtin_amdgcn_s_setprio(0); } while (0)
; #define PG8_WAIT_V(n) asm volatile("s_waitcnt vmcnt(" #n ")" ::: "memory")
; #define PG8_WAIT_L(n) asm volatile("s_waitcnt lgkmcnt(" #n ")" ::: "memory")
; #define PG8_BAR __builtin_amdgcn_s_barrier()
; #define PG8_SCHED __builtin_amdgcn_sched_barrier(0)
; template <class Epi, class Sched>
; DI void gemm_phase(LAS unsigned char* lds, const Sched& S, const Epi& E) {
;     ...
;             PG8_LDB(B0, 1, 0); PG8_LDB(B1, 1, 1); PG8_SCHED; PG8_LDA(At, 1, 0); PG8_STAGE(PG8_SA(0, 1), a2 + hstepA, voffA);
;             PG8_WAIT_V(8); PG8_WAIT_L(0); PG8_BAR; PG8_MMA(0, 0, At, B0); PG8_MMA(0, 1, At, B1); PG8_BAR; PG8_SCHED;
;             PG8_LDA(At, 1, 1); PG8_STAGE(PG8_SB(1, 0), b3, voffB); PG8_STAGE(PG8_SB(1, 1), b3 + hstepB, voffB); PG8_STAGE(PG8_SA(1, 0), a3, voffA);
;             PG8_WAIT_V(8); PG8_WAIT_L(0); PG8_BAR; PG8_MMA(1, 0, At, B0); PG8_MMA(1, 1, At, B1); PG8_BAR; PG8_SCHED;
;         }
;         if (wr == 0) PG8_BAR;
	s_add_i32 s83, 0, 0x18000
	s_add_i32 s85, 0, 0x1c000
	ds_read_b128 v[60:63], v216 offset:32768
	ds_read_b128 v[156:159], v216 offset:33792
	ds_read_b128 v[160:163], v216 offset:34816
	ds_read_b128 v[168:171], v216 offset:35840
	ds_read_b128 v[172:175], v216 offset:49152
	ds_read_b128 v[176:179], v216 offset:50176
	ds_read_b128 v[180:183], v216 offset:51200
	ds_read_b128 v[184:187], v216 offset:52224
	s_add_u32 s40, s40, 0x80000
	s_addc_u32 s41, s41, 0
	s_mov_b32 m0, s64
	ds_read_b128 v[188:191], v166 offset:32768
	ds_read_b128 v[192:195], v166 offset:33792
	ds_read_b128 v[204:207], v166 offset:34816
	ds_read_b128 v[208:211], v166 offset:35840
	ds_read_b128 v[212:215], v166 offset:36864
	ds_read_b128 v[230:233], v166 offset:37888
	ds_read_b128 v[234:237], v166 offset:38912
	global_load_lds_dwordx4 v136, s[40:41]
	s_mov_b32 m0, s65
	ds_read_b128 v[238:241], v166 offset:39936
	global_load_lds_dwordx4 v140, s[40:41]
	s_waitcnt vmcnt(8) lgkmcnt(0)
	s_barrier
	s_setprio 1
	v_mfma_f32_16x16x32_bf16 v[132:135], v[60:63], v[188:191], v[132:135]
	v_mfma_f32_16x16x32_bf16 v[128:131], v[160:163], v[188:191], v[128:131]
	v_mfma_f32_16x16x32_bf16 v[116:119], v[60:63], v[204:207], v[116:119]
	v_mfma_f32_16x16x32_bf16 v[112:115], v[160:163], v[204:207], v[112:115]
	v_mfma_f32_16x16x32_bf16 v[100:103], v[60:63], v[212:215], v[100:103]
	v_mfma_f32_16x16x32_bf16 v[96:99], v[160:163], v[212:215], v[96:99]
	v_mfma_f32_16x16x32_bf16 v[84:87], v[60:63], v[234:237], v[84:87]
	v_mfma_f32_16x16x32_bf16 v[80:83], v[160:163], v[234:237], v[80:83]
	v_mfma_f32_16x16x32_bf16 v[132:135], v[156:159], v[192:195], v[132:135]
	v_mfma_f32_16x16x32_bf16 v[128:131], v[168:171], v[192:195], v[128:131]
	v_mfma_f32_16x16x32_bf16 v[116:119], v[156:159], v[208:211], v[116:119]
	v_mfma_f32_16x16x32_bf16 v[112:115], v[168:171], v[208:211], v[112:115]
	v_mfma_f32_16x16x32_bf16 v[100:103], v[156:159], v[230:233], v[100:103]
	v_mfma_f32_16x16x32_bf16 v[96:99], v[168:171], v[230:233], v[96:99]
	v_mfma_f32_16x16x32_bf16 v[84:87], v[156:159], v[238:241], v[84:87]
	v_mfma_f32_16x16x32_bf16 v[80:83], v[168:171], v[238:241], v[80:83]
	v_mfma_f32_16x16x32_bf16 v[124:127], v[172:175], v[188:191], v[124:127]
	v_mfma_f32_16x16x32_bf16 v[120:123], v[180:183], v[188:191], v[120:123]
	v_mfma_f32_16x16x32_bf16 v[108:111], v[172:175], v[204:207], v[108:111]
	v_mfma_f32_16x16x32_bf16 v[104:107], v[180:183], v[204:207], v[104:107]
	v_mfma_f32_16x16x32_bf16 v[92:95], v[172:175], v[212:215], v[92:95]
	v_mfma_f32_16x16x32_bf16 v[88:91], v[180:183], v[212:215], v[88:91]
	v_mfma_f32_16x16x32_bf16 v[76:79], v[172:175], v[234:237], v[76:79]
	v_mfma_f32_16x16x32_bf16 v[72:75], v[180:183], v[234:237], v[72:75]
	v_mfma_f32_16x16x32_bf16 v[124:127], v[176:179], v[192:195], v[124:127]
	v_mfma_f32_16x16x32_bf16 v[120:123], v[184:187], v[192:195], v[120:123]
	v_mfma_f32_16x16x32_bf16 v[108:111], v[176:179], v[208:211], v[108:111]
	v_mfma_f32_16x16x32_bf16 v[104:107], v[184:187], v[208:211], v[104:107]
	v_mfma_f32_16x16x32_bf16 v[92:95], v[176:179], v[230:233], v[92:95]
	v_mfma_f32_16x16x32_bf16 v[88:91], v[184:187], v[230:233], v[88:91]
	v_mfma_f32_16x16x32_bf16 v[76:79], v[176:179], v[238:241], v[76:79]
	v_mfma_f32_16x16x32_bf16 v[72:75], v[184:187], v[238:241], v[72:75]
	s_setprio 0
	s_barrier
	s_add_i32 s40, s83, s27
	s_add_u32 s8, s8, 0x80
	s_addc_u32 s9, s9, 0
	s_mov_b32 m0, s40
	ds_read_b128 v[188:191], v166 offset:49152
	ds_read_b128 v[192:195], v166 offset:50176
	ds_read_b128 v[204:207], v166 offset:51200
	ds_read_b128 v[208:211], v166 offset:52224
	global_load_lds_dwordx4 v138, s[8:9]
	s_add_i32 m0, s40, 0x2000
	s_add_i32 s40, s85, s27
	global_load_lds_dwordx4 v142, s[8:9]
	s_add_u32 s8, s8, 0x80000
	s_addc_u32 s9, s9, 0
	s_mov_b32 m0, s40
	ds_read_b128 v[238:241], v166 offset:56320
	global_load_lds_dwordx4 v138, s[8:9]
	s_add_i32 m0, s40, 0x2000
	ds_read_b128 v[234:237], v166 offset:55296
	global_load_lds_dwordx4 v142, s[8:9]
	s_mov_b32 m0, s72
	ds_read_b128 v[230:233], v166 offset:54272
	global_load_lds_dwordx4 v136, s[98:99]
	s_mov_b32 m0, s73
	ds_read_b128 v[212:215], v166 offset:53248
	global_load_lds_dwordx4 v140, s[98:99]
	s_waitcnt vmcnt(8) lgkmcnt(0)
	s_barrier
	s_setprio 1
	v_mfma_f32_16x16x32_bf16 v[68:71], v[60:63], v[188:191], v[68:71]
	v_mfma_f32_16x16x32_bf16 v[64:67], v[160:163], v[188:191], v[64:67]
	v_mfma_f32_16x16x32_bf16 v[48:51], v[60:63], v[204:207], v[48:51]
	v_mfma_f32_16x16x32_bf16 v[44:47], v[160:163], v[204:207], v[44:47]
	v_mfma_f32_16x16x32_bf16 v[32:35], v[60:63], v[212:215], v[32:35]
	v_mfma_f32_16x16x32_bf16 v[28:31], v[160:163], v[212:215], v[28:31]
	v_mfma_f32_16x16x32_bf16 v[16:19], v[60:63], v[234:237], v[16:19]
	v_mfma_f32_16x16x32_bf16 v[12:15], v[160:163], v[234:237], v[12:15]
	v_mfma_f32_16x16x32_bf16 v[68:71], v[156:159], v[192:195], v[68:71]
	v_mfma_f32_16x16x32_bf16 v[64:67], v[168:171], v[192:195], v[64:67]
	v_mfma_f32_16x16x32_bf16 v[48:51], v[156:159], v[208:211], v[48:51]
	v_mfma_f32_16x16x32_bf16 v[44:47], v[168:171], v[208:211], v[44:47]
	v_mfma_f32_16x16x32_bf16 v[32:35], v[156:159], v[230:233], v[32:35]
	v_mfma_f32_16x16x32_bf16 v[28:31], v[168:171], v[230:233], v[28:31]
	v_mfma_f32_16x16x32_bf16 v[16:19], v[156:159], v[238:241], v[16:19]
	v_mfma_f32_16x16x32_bf16 v[12:15], v[168:171], v[238:241], v[12:15]
	v_mfma_f32_16x16x32_bf16 v[52:55], v[172:175], v[188:191], v[52:55]
	v_mfma_f32_16x16x32_bf16 v[60:63], v[176:179], v[192:195], v[52:55]
	v_mfma_f32_16x16x32_bf16 v[52:55], v[180:183], v[188:191], v[56:59]
	v_mfma_f32_16x16x32_bf16 v[40:43], v[172:175], v[204:207], v[40:43]
	v_mfma_f32_16x16x32_bf16 v[36:39], v[180:183], v[204:207], v[36:39]
	v_mfma_f32_16x16x32_bf16 v[24:27], v[172:175], v[212:215], v[24:27]
	v_mfma_f32_16x16x32_bf16 v[20:23], v[180:183], v[212:215], v[20:23]
	v_mfma_f32_16x16x32_bf16 v[8:11], v[172:175], v[234:237], v[8:11]
	v_mfma_f32_16x16x32_bf16 v[4:7], v[180:183], v[234:237], v[4:7]
	v_mfma_f32_16x16x32_bf16 v[56:59], v[184:187], v[192:195], v[52:55]
	v_mfma_f32_16x16x32_bf16 v[40:43], v[176:179], v[208:211], v[40:43]
	v_mfma_f32_16x16x32_bf16 v[36:39], v[184:187], v[208:211], v[36:39]
	v_mfma_f32_16x16x32_bf16 v[24:27], v[176:179], v[230:233], v[24:27]
	v_mfma_f32_16x16x32_bf16 v[20:23], v[184:187], v[230:233], v[20:23]
	v_mfma_f32_16x16x32_bf16 v[8:11], v[176:179], v[238:241], v[8:11]
	v_mfma_f32_16x16x32_bf16 v[4:7], v[184:187], v[238:241], v[4:7]
	s_setprio 0
	s_barrier
	s_add_u32 s80, s80, 0x100
	s_addc_u32 s81, s81, 0
	s_add_u32 s4, s4, 0x100
	s_addc_u32 s5, s5, 0
	s_cmp_ge_i32 s82, s35
	s_mov_b32 s8, s82
	s_cbranch_scc0 .LBB0_156
	s_and_b64 vcc, exec, s[48:49]
	s_cbranch_vccz .LBB0_159
	s_barrier

; #define PG8_STAGE(bufoff, gbase, voff) do { _Pragma("unroll") for (int _i = 0; _i < 2; ++_i) \
;         __builtin_amdgcn_global_load_lds((const unsigned*)((const char*)(gbase) + (voff)[_i]), (LAS unsigned*)(lds + (bufoff) + ldsw + _i * 8192), 16, 0, 0); } while (0)
; #define PG8_LDA(dst, b, h) do { _Pragma("unroll") for (int m = 0; m < 4; ++m) _Pragma("unroll") for (int k = 0; k < 2; ++k) dst[m][k] = *(const LAS bf16x8*)(lds + PG8_SA(b, h) + aoff + m * 2048 + k * 1024); } while (0)
; #define PG8_LDB(dst, b, h) do { _Pragma("unroll") for (int n = 0; n < 2; ++n) _Pragma("unroll") for (int k = 0; k < 2; ++k) dst[n][k] = *(const LAS bf16x8*)(lds + PG8_SB(b, h) + boff + n * 2048 + k * 1024); } while (0)
; #define PG8_MMA(ai, bj, At, Bt) do { __builtin_amdgcn_s_setprio(1); _Pragma("unroll") for (int m = 0; m < 4; ++m) _Pragma("unroll") for (int n = 0; n < 2; ++n) _Pragma("unroll") for (int k = 0; k < 2; ++k) \
;         acc[ai][bj][m][n] = __builtin_amdgcn_mfma_f32_16x16x32_bf16(Bt[n][k], At[m][k], acc[ai][bj][m][n], 0, 0, 0); __builtin_amdgcn_s_setprio(0); } while (0)
; #define PG8_WAIT_V(n) asm volatile("s_waitcnt vmcnt(" #n ")" ::: "memory")
; #define PG8_WAIT_L(n) asm volatile("s_waitcnt lgkmcnt(" #n ")" ::: "memory")
; #define PG8_BAR __builtin_amdgcn_s_barrier()
; template <class Epi, class Sched>
; DI void gemm_phase(LAS unsigned char* lds, const Sched& S, const Epi& E) {
;     ...
;         for (int t = 0; t < nt; t += 2) {
;             const bool last = (t == nt - 2);
;             const char* a1 = cA + (size_t)(t + 1) * kstep;
;             const char* a2 = last ? nA : cA + (size_t)(t + 2) * kstep; const char* b2 = last ? nB : cB + (size_t)(t + 2) * kstep;
;             const char* a3 = a2 + kstep; const char* b3 = b2 + kstep;
;             if constexpr (Epi::HOOK) { if (cur.ks < 0 && (t == 16 || t == 32)) E.hook(acc, cur, t >> 4, wr, wc, fr, fq); }
;             PG8_LDB(B0, 0, 0); PG8_LDB(B1, 0, 1); PG8_SCHED; PG8_LDA(At, 0, 0); PG8_STAGE(PG8_SA(1, 1), a1 + hstepA, voffA);
;             PG8_WAIT_V(8); PG8_WAIT_L(0); PG8_BAR; PG8_MMA(0, 0, At, B0); PG8_MMA(0, 1, At, B1); PG8_BAR; PG8_SCHED;
;             PG8_LDA(At, 0, 1); PG8_STAGE(PG8_SB(0, 0), b2, voffB); PG8_STAGE(PG8_SB(0, 1), b2 + hstepB, voffB); PG8_STAGE(PG8_SA(0, 0), a2, voffA);
;             PG8_WAIT_V(8); PG8_WAIT_L(0); PG8_BAR; PG8_MMA(1, 0, At, B0); PG8_MMA(1, 1, At, B1); PG8_BAR; PG8_SCHED;
.LBB0_906:
	v_add_u32_e32 v158, 0x10000, v162
	s_add_i32 s23, s18, 2
	s_add_u32 s4, s40, 0x100
	s_addc_u32 s5, s41, 0
	s_cmp_eq_u32 s97, s18
	s_cselect_b32 s19, s79, s5
	s_cselect_b32 s18, s26, s4
	s_cselect_b32 s9, s27, s67
	s_cselect_b32 s8, s80, s66
	s_add_i32 s85, 0, 0x10000
	s_add_i32 vcc_lo, 0, 0x14000
	ds_read_b128 v[134:137], v158
	ds_read_b128 v[138:141], v158 offset:1024
	ds_read_b128 v[166:169], v158 offset:2048
	ds_read_b128 v[170:173], v158 offset:3072
	ds_read_b128 v[174:177], v158 offset:16384
	ds_read_b128 v[178:181], v158 offset:17408
	ds_read_b128 v[182:185], v158 offset:18432
	ds_read_b128 v[186:189], v158 offset:19456
	s_add_i32 m0, s39, 0xc000
	ds_read_b128 v[190:193], v164
	ds_read_b128 v[204:207], v164 offset:1024
	ds_read_b128 v[208:211], v164 offset:2048
	ds_read_b128 v[212:215], v164 offset:3072
	ds_read_b128 v[230:233], v164 offset:4096
	ds_read_b128 v[234:237], v164 offset:5120
	ds_read_b128 v[238:241], v164 offset:6144
	global_load_lds_dwordx4 v156, s[40:41]
	s_add_i32 m0, s39, 0xe000
	ds_read_b128 v[242:245], v164 offset:7168
	global_load_lds_dwordx4 v154, s[40:41]
	s_waitcnt vmcnt(8) lgkmcnt(0)
	s_barrier
	s_setprio 1
	v_mfma_f32_16x16x32_bf16 v[130:133], v[134:137], v[190:193], v[130:133]
	v_mfma_f32_16x16x32_bf16 v[126:129], v[166:169], v[190:193], v[126:129]
	v_mfma_f32_16x16x32_bf16 v[114:117], v[134:137], v[208:211], v[114:117]
	v_mfma_f32_16x16x32_bf16 v[110:113], v[166:169], v[208:211], v[110:113]
	v_mfma_f32_16x16x32_bf16 v[98:101], v[134:137], v[230:233], v[98:101]
	v_mfma_f32_16x16x32_bf16 v[94:97], v[166:169], v[230:233], v[94:97]
	v_mfma_f32_16x16x32_bf16 v[82:85], v[134:137], v[238:241], v[82:85]
	v_mfma_f32_16x16x32_bf16 v[78:81], v[166:169], v[238:241], v[78:81]
	v_mfma_f32_16x16x32_bf16 v[130:133], v[138:141], v[204:207], v[130:133]
	v_mfma_f32_16x16x32_bf16 v[126:129], v[170:173], v[204:207], v[126:129]
	v_mfma_f32_16x16x32_bf16 v[114:117], v[138:141], v[212:215], v[114:117]
	v_mfma_f32_16x16x32_bf16 v[110:113], v[170:173], v[212:215], v[110:113]
	v_mfma_f32_16x16x32_bf16 v[98:101], v[138:141], v[234:237], v[98:101]
	v_mfma_f32_16x16x32_bf16 v[94:97], v[170:173], v[234:237], v[94:97]
	v_mfma_f32_16x16x32_bf16 v[82:85], v[138:141], v[242:245], v[82:85]
	v_mfma_f32_16x16x32_bf16 v[78:81], v[170:173], v[242:245], v[78:81]
	v_mfma_f32_16x16x32_bf16 v[122:125], v[174:177], v[190:193], v[122:125]
	v_mfma_f32_16x16x32_bf16 v[118:121], v[182:185], v[190:193], v[118:121]
	v_mfma_f32_16x16x32_bf16 v[106:109], v[174:177], v[208:211], v[106:109]
	v_mfma_f32_16x16x32_bf16 v[102:105], v[182:185], v[208:211], v[102:105]
	v_mfma_f32_16x16x32_bf16 v[90:93], v[174:177], v[230:233], v[90:93]
	v_mfma_f32_16x16x32_bf16 v[86:89], v[182:185], v[230:233], v[86:89]
	v_mfma_f32_16x16x32_bf16 v[74:77], v[174:177], v[238:241], v[74:77]
	v_mfma_f32_16x16x32_bf16 v[70:73], v[182:185], v[238:241], v[70:73]
	v_mfma_f32_16x16x32_bf16 v[122:125], v[178:181], v[204:207], v[122:125]
	v_mfma_f32_16x16x32_bf16 v[118:121], v[186:189], v[204:207], v[118:121]
	v_mfma_f32_16x16x32_bf16 v[106:109], v[178:181], v[212:215], v[106:109]
	v_mfma_f32_16x16x32_bf16 v[102:105], v[186:189], v[212:215], v[102:105]
	v_mfma_f32_16x16x32_bf16 v[90:93], v[178:181], v[234:237], v[90:93]
	v_mfma_f32_16x16x32_bf16 v[86:89], v[186:189], v[234:237], v[86:89]
	v_mfma_f32_16x16x32_bf16 v[74:77], v[178:181], v[242:245], v[74:77]
	v_mfma_f32_16x16x32_bf16 v[70:73], v[186:189], v[242:245], v[70:73]
	s_setprio 0
	s_barrier
	s_add_i32 s40, s85, s38
	s_mov_b32 m0, s40
	ds_read_b128 v[190:193], v164 offset:16384
	ds_read_b128 v[204:207], v164 offset:17408
	ds_read_b128 v[208:211], v164 offset:18432
	ds_read_b128 v[212:215], v164 offset:19456
	global_load_lds_dwordx4 v144, s[8:9]
	s_add_i32 m0, s40, 0x2000
	s_add_u32 s40, s8, 0xc0000
	s_addc_u32 s41, s9, 0
	s_add_i32 s85, vcc_lo, s38
	global_load_lds_dwordx4 v148, s[8:9]
	s_mov_b32 m0, s85
	ds_read_b128 v[242:245], v164 offset:23552
	global_load_lds_dwordx4 v144, s[40:41]
	s_add_i32 m0, s85, 0x2000
	ds_read_b128 v[238:241], v164 offset:22528
	global_load_lds_dwordx4 v148, s[40:41]
	s_add_u32 s98, s18, 0x80
	s_addc_u32 s99, s19, 0
	s_mov_b32 m0, s39
	ds_read_b128 v[234:237], v164 offset:21504
	global_load_lds_dwordx4 v142, s[18:19]
	s_mov_b32 m0, s63
	ds_read_b128 v[230:233], v164 offset:20480
	global_load_lds_dwordx4 v146, s[18:19]
	s_waitcnt vmcnt(8) lgkmcnt(0)
	s_barrier
	s_setprio 1
	v_mfma_f32_16x16x32_bf16 v[66:69], v[134:137], v[190:193], v[66:69]
	v_mfma_f32_16x16x32_bf16 v[62:65], v[166:169], v[190:193], v[62:65]
	v_mfma_f32_16x16x32_bf16 v[50:53], v[134:137], v[208:211], v[50:53]
	v_mfma_f32_16x16x32_bf16 v[46:49], v[166:169], v[208:211], v[46:49]
	v_mfma_f32_16x16x32_bf16 v[34:37], v[134:137], v[230:233], v[34:37]
	v_mfma_f32_16x16x32_bf16 v[30:33], v[166:169], v[230:233], v[30:33]
	v_mfma_f32_16x16x32_bf16 v[18:21], v[134:137], v[238:241], v[18:21]
	v_mfma_f32_16x16x32_bf16 v[14:17], v[166:169], v[238:241], v[14:17]
	v_mfma_f32_16x16x32_bf16 v[66:69], v[138:141], v[204:207], v[66:69]
	v_mfma_f32_16x16x32_bf16 v[62:65], v[170:173], v[204:207], v[62:65]
	v_mfma_f32_16x16x32_bf16 v[50:53], v[138:141], v[212:215], v[50:53]
	v_mfma_f32_16x16x32_bf16 v[46:49], v[170:173], v[212:215], v[46:49]
	v_mfma_f32_16x16x32_bf16 v[34:37], v[138:141], v[234:237], v[34:37]
	v_mfma_f32_16x16x32_bf16 v[30:33], v[170:173], v[234:237], v[30:33]
	v_mfma_f32_16x16x32_bf16 v[18:21], v[138:141], v[242:245], v[18:21]
	v_mfma_f32_16x16x32_bf16 v[14:17], v[170:173], v[242:245], v[14:17]
	v_mfma_f32_16x16x32_bf16 v[58:61], v[174:177], v[190:193], v[58:61]
	v_mfma_f32_16x16x32_bf16 v[54:57], v[182:185], v[190:193], v[54:57]
	v_mfma_f32_16x16x32_bf16 v[42:45], v[174:177], v[208:211], v[42:45]
	v_mfma_f32_16x16x32_bf16 v[38:41], v[182:185], v[208:211], v[38:41]
	v_mfma_f32_16x16x32_bf16 v[26:29], v[174:177], v[230:233], v[26:29]
	v_mfma_f32_16x16x32_bf16 v[22:25], v[182:185], v[230:233], v[22:25]
	v_mfma_f32_16x16x32_bf16 v[10:13], v[174:177], v[238:241], v[10:13]
	v_mfma_f32_16x16x32_bf16 v[4:7], v[182:185], v[238:241], v[6:9]
	v_mfma_f32_16x16x32_bf16 v[58:61], v[178:181], v[204:207], v[58:61]
	v_mfma_f32_16x16x32_bf16 v[54:57], v[186:189], v[204:207], v[54:57]
	v_mfma_f32_16x16x32_bf16 v[42:45], v[178:181], v[212:215], v[42:45]
	v_mfma_f32_16x16x32_bf16 v[38:41], v[186:189], v[212:215], v[38:41]
	v_mfma_f32_16x16x32_bf16 v[26:29], v[178:181], v[234:237], v[26:29]
	v_mfma_f32_16x16x32_bf16 v[22:25], v[186:189], v[234:237], v[22:25]
	v_mfma_f32_16x16x32_bf16 v[10:13], v[178:181], v[242:245], v[10:13]
	v_mfma_f32_16x16x32_bf16 v[4:7], v[186:189], v[242:245], v[4:7]
	s_setprio 0
	s_barrier
; #define PG8_STAGE(bufoff, gbase, voff) do { _Pragma("unroll") for (int _i = 0; _i < 2; ++_i) \
;         __builtin_amdgcn_global_load_lds((const unsigned*)((const char*)(gbase) + (voff)[_i]), (LAS unsigned*)(lds + (bufoff) + ldsw + _i * 8192), 16, 0, 0); } while (0)
; #define PG8_LDA(dst, b, h) do { _Pragma("unroll") for (int m = 0; m < 4; ++m) _Pragma("unroll") for (int k = 0; k < 2; ++k) dst[m][k] = *(const LAS bf16x8*)(lds + PG8_SA(b, h) + aoff + m * 2048 + k * 1024); } while (0)
; #define PG8_LDB(dst, b, h) do { _Pragma("unroll") for (int n = 0; n < 2; ++n) _Pragma("unroll") for (int k = 0; k < 2; ++k) dst[n][k] = *(const LAS bf16x8*)(lds + PG8_SB(b, h) + boff + n * 2048 + k * 1024); } while (0)
; #define PG8_MMA(ai, bj, At, Bt) do { __builtin_amdgcn_s_setprio(1); _Pragma("unroll") for (int m = 0; m < 4; ++m) _Pragma("unroll") for (int n = 0; n < 2; ++n) _Pragma("unroll") for (int k = 0; k < 2; ++k) \
;         acc[ai][bj][m][n] = __builtin_amdgcn_mfma_f32_16x16x32_bf16(Bt[n][k], At[m][k], acc[ai][bj][m][n], 0, 0, 0); __builtin_amdgcn_s_setprio(0); } while (0)
; template <class Epi, class Sched>
; DI void gemm_phase(LAS unsigned char* lds, const Sched& S, const Epi& E) {
;     ...
;             if constexpr (Epi::HOOK) { if (cur.ks < 0 && (t == 16 || t == 32)) E.hook(acc, cur, t >> 4, wr, wc, fr, fq); }
;             PG8_LDB(B0, 0, 0); PG8_LDB(B1, 0, 1); PG8_SCHED; PG8_LDA(At, 0, 0); PG8_STAGE(PG8_SA(1, 1), a1 + hstepA, voffA);
;             PG8_WAIT_V(8); PG8_WAIT_L(0); PG8_BAR; PG8_MMA(0, 0, At, B0); PG8_MMA(0, 1, At, B1); PG8_BAR; PG8_SCHED;
;             PG8_LDA(At, 0, 1); PG8_STAGE(PG8_SB(0, 0), b2, voffB); PG8_STAGE(PG8_SB(0, 1), b2 + hstepB, voffB); PG8_STAGE(PG8_SA(0, 0), a2, voffA);
;             PG8_WAIT_V(8); PG8_WAIT_L(0); PG8_BAR; PG8_MMA(1, 0, At, B0); PG8_MMA(1, 1, At, B1); PG8_BAR; PG8_SCHED;
;             PG8_LDB(B0, 1, 0); PG8_LDB(B1, 1, 1); PG8_SCHED; PG8_LDA(At, 1, 0); PG8_STAGE(PG8_SA(0, 1), a2 + hstepA, voffA);
;             PG8_WAIT_V(8); PG8_WAIT_L(0); PG8_BAR; PG8_MMA(0, 0, At, B0); PG8_MMA(0, 1, At, B1); PG8_BAR; PG8_SCHED;
;             PG8_LDA(At, 1, 1); PG8_STAGE(PG8_SB(1, 0), b3, voffB); PG8_STAGE(PG8_SB(1, 1), b3 + hstepB, voffB); PG8_STAGE(PG8_SA(1, 0), a3, voffA);
;             PG8_WAIT_V(8); PG8_WAIT_L(0); PG8_BAR; PG8_MMA(1, 0, At, B0); PG8_MMA(1, 1, At, B1); PG8_BAR; PG8_SCHED;
;         }
	s_add_i32 s40, 0, 0x18000
	s_add_i32 s41, 0, 0x1c000
	ds_read_b128 v[134:137], v158 offset:32768
	ds_read_b128 v[138:141], v158 offset:33792
	ds_read_b128 v[166:169], v158 offset:34816
	ds_read_b128 v[170:173], v158 offset:35840
	ds_read_b128 v[174:177], v158 offset:49152
	ds_read_b128 v[178:181], v158 offset:50176
	ds_read_b128 v[182:185], v158 offset:51200
	ds_read_b128 v[186:189], v158 offset:52224
	s_add_u32 s18, s18, 0xc0000
	s_addc_u32 s19, s19, 0
	s_mov_b32 m0, s64
	ds_read_b128 v[190:193], v164 offset:32768
	ds_read_b128 v[204:207], v164 offset:33792
	ds_read_b128 v[208:211], v164 offset:34816
	ds_read_b128 v[212:215], v164 offset:35840
	ds_read_b128 v[230:233], v164 offset:36864
	ds_read_b128 v[234:237], v164 offset:37888
	ds_read_b128 v[238:241], v164 offset:38912
	global_load_lds_dwordx4 v142, s[18:19]
	s_mov_b32 m0, s65
	ds_read_b128 v[242:245], v164 offset:39936
	global_load_lds_dwordx4 v146, s[18:19]
	s_waitcnt vmcnt(8) lgkmcnt(0)
	s_barrier
	s_setprio 1
	v_mfma_f32_16x16x32_bf16 v[130:133], v[134:137], v[190:193], v[130:133]
	v_mfma_f32_16x16x32_bf16 v[126:129], v[166:169], v[190:193], v[126:129]
	v_mfma_f32_16x16x32_bf16 v[114:117], v[134:137], v[208:211], v[114:117]
	v_mfma_f32_16x16x32_bf16 v[110:113], v[166:169], v[208:211], v[110:113]
	v_mfma_f32_16x16x32_bf16 v[98:101], v[134:137], v[230:233], v[98:101]
	v_mfma_f32_16x16x32_bf16 v[94:97], v[166:169], v[230:233], v[94:97]
	v_mfma_f32_16x16x32_bf16 v[82:85], v[134:137], v[238:241], v[82:85]
	v_mfma_f32_16x16x32_bf16 v[78:81], v[166:169], v[238:241], v[78:81]
	v_mfma_f32_16x16x32_bf16 v[130:133], v[138:141], v[204:207], v[130:133]
	v_mfma_f32_16x16x32_bf16 v[126:129], v[170:173], v[204:207], v[126:129]
	v_mfma_f32_16x16x32_bf16 v[114:117], v[138:141], v[212:215], v[114:117]
	v_mfma_f32_16x16x32_bf16 v[110:113], v[170:173], v[212:215], v[110:113]
	v_mfma_f32_16x16x32_bf16 v[98:101], v[138:141], v[234:237], v[98:101]
	v_mfma_f32_16x16x32_bf16 v[94:97], v[170:173], v[234:237], v[94:97]
	v_mfma_f32_16x16x32_bf16 v[82:85], v[138:141], v[242:245], v[82:85]
	v_mfma_f32_16x16x32_bf16 v[78:81], v[170:173], v[242:245], v[78:81]
	v_mfma_f32_16x16x32_bf16 v[122:125], v[174:177], v[190:193], v[122:125]
	v_mfma_f32_16x16x32_bf16 v[118:121], v[182:185], v[190:193], v[118:121]
	v_mfma_f32_16x16x32_bf16 v[106:109], v[174:177], v[208:211], v[106:109]
	v_mfma_f32_16x16x32_bf16 v[102:105], v[182:185], v[208:211], v[102:105]
	v_mfma_f32_16x16x32_bf16 v[90:93], v[174:177], v[230:233], v[90:93]
	v_mfma_f32_16x16x32_bf16 v[86:89], v[182:185], v[230:233], v[86:89]
	v_mfma_f32_16x16x32_bf16 v[74:77], v[174:177], v[238:241], v[74:77]
	v_mfma_f32_16x16x32_bf16 v[70:73], v[182:185], v[238:241], v[70:73]
	v_mfma_f32_16x16x32_bf16 v[122:125], v[178:181], v[204:207], v[122:125]
	v_mfma_f32_16x16x32_bf16 v[118:121], v[186:189], v[204:207], v[118:121]
	v_mfma_f32_16x16x32_bf16 v[106:109], v[178:181], v[212:215], v[106:109]
	v_mfma_f32_16x16x32_bf16 v[102:105], v[186:189], v[212:215], v[102:105]
	v_mfma_f32_16x16x32_bf16 v[90:93], v[178:181], v[234:237], v[90:93]
	v_mfma_f32_16x16x32_bf16 v[86:89], v[186:189], v[234:237], v[86:89]
	v_mfma_f32_16x16x32_bf16 v[74:77], v[178:181], v[242:245], v[74:77]
	v_mfma_f32_16x16x32_bf16 v[70:73], v[186:189], v[242:245], v[70:73]
	s_setprio 0
	s_barrier
	s_add_i32 s18, s40, s38
	s_add_u32 s8, s8, 0x80
	s_addc_u32 s9, s9, 0
	s_mov_b32 m0, s18
	ds_read_b128 v[190:193], v164 offset:49152
	ds_read_b128 v[204:207], v164 offset:50176
	ds_read_b128 v[208:211], v164 offset:51200
	ds_read_b128 v[212:215], v164 offset:52224
	global_load_lds_dwordx4 v144, s[8:9]
	s_add_i32 m0, s18, 0x2000
	s_add_i32 s18, s41, s38
	global_load_lds_dwordx4 v148, s[8:9]
	s_add_u32 s8, s8, 0xc0000
	s_addc_u32 s9, s9, 0
	s_mov_b32 m0, s18
	ds_read_b128 v[242:245], v164 offset:56320
	global_load_lds_dwordx4 v144, s[8:9]
	s_add_i32 m0, s18, 0x2000
	ds_read_b128 v[238:241], v164 offset:55296
	global_load_lds_dwordx4 v148, s[8:9]
	s_mov_b32 m0, s75
	ds_read_b128 v[234:237], v164 offset:54272
	global_load_lds_dwordx4 v142, s[98:99]
	s_mov_b32 m0, s81
	ds_read_b128 v[230:233], v164 offset:53248
	global_load_lds_dwordx4 v146, s[98:99]
	s_waitcnt vmcnt(8) lgkmcnt(0)
	s_barrier
	s_setprio 1
	v_mfma_f32_16x16x32_bf16 v[66:69], v[134:137], v[190:193], v[66:69]
	v_mfma_f32_16x16x32_bf16 v[62:65], v[166:169], v[190:193], v[62:65]
	v_mfma_f32_16x16x32_bf16 v[50:53], v[134:137], v[208:211], v[50:53]
	v_mfma_f32_16x16x32_bf16 v[46:49], v[166:169], v[208:211], v[46:49]
	v_mfma_f32_16x16x32_bf16 v[34:37], v[134:137], v[230:233], v[34:37]
	v_mfma_f32_16x16x32_bf16 v[30:33], v[166:169], v[230:233], v[30:33]
	v_mfma_f32_16x16x32_bf16 v[18:21], v[134:137], v[238:241], v[18:21]
	v_mfma_f32_16x16x32_bf16 v[14:17], v[166:169], v[238:241], v[14:17]
	v_mfma_f32_16x16x32_bf16 v[66:69], v[138:141], v[204:207], v[66:69]
	v_mfma_f32_16x16x32_bf16 v[62:65], v[170:173], v[204:207], v[62:65]
	v_mfma_f32_16x16x32_bf16 v[50:53], v[138:141], v[212:215], v[50:53]
	v_mfma_f32_16x16x32_bf16 v[46:49], v[170:173], v[212:215], v[46:49]
	v_mfma_f32_16x16x32_bf16 v[34:37], v[138:141], v[234:237], v[34:37]
	v_mfma_f32_16x16x32_bf16 v[30:33], v[170:173], v[234:237], v[30:33]
	v_mfma_f32_16x16x32_bf16 v[18:21], v[138:141], v[242:245], v[18:21]
	v_mfma_f32_16x16x32_bf16 v[14:17], v[170:173], v[242:245], v[14:17]
	v_mfma_f32_16x16x32_bf16 v[58:61], v[174:177], v[190:193], v[58:61]
	v_mfma_f32_16x16x32_bf16 v[54:57], v[182:185], v[190:193], v[54:57]
	v_mfma_f32_16x16x32_bf16 v[42:45], v[174:177], v[208:211], v[42:45]
	v_mfma_f32_16x16x32_bf16 v[38:41], v[182:185], v[208:211], v[38:41]
	v_mfma_f32_16x16x32_bf16 v[26:29], v[174:177], v[230:233], v[26:29]
	v_mfma_f32_16x16x32_bf16 v[22:25], v[182:185], v[230:233], v[22:25]
	v_mfma_f32_16x16x32_bf16 v[8:11], v[174:177], v[238:241], v[10:13]
	v_mfma_f32_16x16x32_bf16 v[4:7], v[182:185], v[238:241], v[4:7]
	v_mfma_f32_16x16x32_bf16 v[58:61], v[178:181], v[204:207], v[58:61]
	v_mfma_f32_16x16x32_bf16 v[54:57], v[186:189], v[204:207], v[54:57]
	v_mfma_f32_16x16x32_bf16 v[42:45], v[178:181], v[212:215], v[42:45]
	v_mfma_f32_16x16x32_bf16 v[38:41], v[186:189], v[212:215], v[38:41]
	v_mfma_f32_16x16x32_bf16 v[26:29], v[178:181], v[234:237], v[26:29]
	v_mfma_f32_16x16x32_bf16 v[22:25], v[186:189], v[234:237], v[22:25]
	v_mfma_f32_16x16x32_bf16 v[10:13], v[178:181], v[242:245], v[8:11]
	v_mfma_f32_16x16x32_bf16 v[6:9], v[186:189], v[242:245], v[4:7]
	s_setprio 0
	s_barrier
	s_add_i32 s22, s22, 1
	s_add_u32 s66, s66, 0x100
	s_addc_u32 s67, s67, 0
	s_cmp_ge_i32 s23, s10
	s_cbranch_scc1 .LBB0_908
	s_mov_b64 s[40:41], s[4:5]
	s_mov_b32 s18, s23
	s_andn2_b64 vcc, exec, s[56:57]
	s_cbranch_vccnz .LBB0_906
	s_branch .LBB0_900

; #define PG8_STAGE(bufoff, gbase, voff) do { _Pragma("unroll") for (int _i = 0; _i < 2; ++_i) \
;         __builtin_amdgcn_global_load_lds((const unsigned*)((const char*)(gbase) + (voff)[_i]), (LAS unsigned*)(lds + (bufoff) + ldsw + _i * 8192), 16, 0, 0); } while (0)
; #define PG8_LDA(dst, b, h) do { _Pragma("unroll") for (int m = 0; m < 4; ++m) _Pragma("unroll") for (int k = 0; k < 2; ++k) dst[m][k] = *(const LAS bf16x8*)(lds + PG8_SA(b, h) + aoff + m * 2048 + k * 1024); } while (0)
; #define PG8_LDB(dst, b, h) do { _Pragma("unroll") for (int n = 0; n < 2; ++n) _Pragma("unroll") for (int k = 0; k < 2; ++k) dst[n][k] = *(const LAS bf16x8*)(lds + PG8_SB(b, h) + boff + n * 2048 + k * 1024); } while (0)
; #define PG8_MMA(ai, bj, At, Bt) do { __builtin_amdgcn_s_setprio(1); _Pragma("unroll") for (int m = 0; m < 4; ++m) _Pragma("unroll") for (int n = 0; n < 2; ++n) _Pragma("unroll") for (int k = 0; k < 2; ++k) \
;         acc[ai][bj][m][n] = __builtin_amdgcn_mfma_f32_16x16x32_bf16(Bt[n][k], At[m][k], acc[ai][bj][m][n], 0, 0, 0); __builtin_amdgcn_s_setprio(0); } while (0)
; #define PG8_WAIT_V(n) asm volatile("s_waitcnt vmcnt(" #n ")" ::: "memory")
; #define PG8_WAIT_L(n) asm volatile("s_waitcnt lgkmcnt(" #n ")" ::: "memory")
; #define PG8_BAR __builtin_amdgcn_s_barrier()
; template <class Epi, class Sched>
; DI void gemm_phase(LAS unsigned char* lds, const Sched& S, const Epi& E) {
;     ...
;         for (int t = 0; t < nt; t += 2) {
;             const bool last = (t == nt - 2);
;             const char* a1 = cA + (size_t)(t + 1) * kstep;
;             const char* a2 = last ? nA : cA + (size_t)(t + 2) * kstep; const char* b2 = last ? nB : cB + (size_t)(t + 2) * kstep;
;             const char* a3 = a2 + kstep; const char* b3 = b2 + kstep;
;             if constexpr (Epi::HOOK) { if (cur.ks < 0 && (t == 16 || t == 32)) E.hook(acc, cur, t >> 4, wr, wc, fr, fq); }
;             PG8_LDB(B0, 0, 0); PG8_LDB(B1, 0, 1); PG8_SCHED; PG8_LDA(At, 0, 0); PG8_STAGE(PG8_SA(1, 1), a1 + hstepA, voffA);
;             PG8_WAIT_V(8); PG8_WAIT_L(0); PG8_BAR; PG8_MMA(0, 0, At, B0); PG8_MMA(0, 1, At, B1); PG8_BAR; PG8_SCHED;
;             PG8_LDA(At, 0, 1); PG8_STAGE(PG8_SB(0, 0), b2, voffB); PG8_STAGE(PG8_SB(0, 1), b2 + hstepB, voffB); PG8_STAGE(PG8_SA(0, 0), a2, voffA);
;             PG8_WAIT_V(8); PG8_WAIT_L(0); PG8_BAR; PG8_MMA(1, 0, At, B0); PG8_MMA(1, 1, At, B1); PG8_BAR; PG8_SCHED;
.LBB0_1104:
	v_add_u32_e32 v214, 0x10000, v197
	s_add_i32 s82, s52, 2
	s_add_u32 s53, s42, 0xfff80080
	s_addc_u32 s54, s43, -1
	s_add_i32 s83, 0, 0x10000
	s_cmp_eq_u32 s79, s52
	s_cselect_b32 s55, s56, s54
	s_cselect_b32 s54, s57, s53
	s_cselect_b32 s53, s58, s81
	s_cselect_b32 s52, s59, s80
	s_add_i32 s85, 0, 0x14000
	s_waitcnt vmcnt(0)
	ds_read_b128 v[84:87], v214
	ds_read_b128 v[88:91], v214 offset:1024
	ds_read_b128 v[104:107], v214 offset:2048
	ds_read_b128 v[112:115], v214 offset:3072
	ds_read_b128 v[124:127], v214 offset:16384
	ds_read_b128 v[136:139], v214 offset:17408
	ds_read_b128 v[148:151], v214 offset:18432
	ds_read_b128 v[160:163], v214 offset:19456
	s_add_i32 m0, s26, 0xc000
	ds_read_b128 v[164:167], v231
	ds_read_b128 v[168:171], v231 offset:1024
	ds_read_b128 v[172:175], v231 offset:2048
	ds_read_b128 v[176:179], v231 offset:3072
	ds_read_b128 v[180:183], v231 offset:4096
	ds_read_b128 v[184:187], v231 offset:5120
	ds_read_b128 v[188:191], v231 offset:6144
	global_load_lds_dwordx4 v212, s[42:43]
	s_add_i32 m0, s26, 0xe000
	ds_read_b128 v[192:195], v231 offset:7168
	global_load_lds_dwordx4 v210, s[42:43]
	s_waitcnt vmcnt(8) lgkmcnt(0)
	s_barrier
	s_setprio 1
	v_mfma_f32_16x16x32_bf16 v[156:159], v[84:87], v[164:167], v[156:159]
	v_mfma_f32_16x16x32_bf16 v[152:155], v[104:107], v[164:167], v[152:155]
	v_mfma_f32_16x16x32_bf16 v[132:135], v[84:87], v[172:175], v[132:135]
	v_mfma_f32_16x16x32_bf16 v[128:131], v[104:107], v[172:175], v[128:131]
	v_mfma_f32_16x16x32_bf16 v[108:111], v[84:87], v[180:183], v[108:111]
	v_mfma_f32_16x16x32_bf16 v[100:103], v[104:107], v[180:183], v[100:103]
	v_mfma_f32_16x16x32_bf16 v[80:83], v[84:87], v[188:191], v[80:83]
	v_mfma_f32_16x16x32_bf16 v[76:79], v[104:107], v[188:191], v[76:79]
	v_mfma_f32_16x16x32_bf16 v[156:159], v[88:91], v[168:171], v[156:159]
	v_mfma_f32_16x16x32_bf16 v[152:155], v[112:115], v[168:171], v[152:155]
	v_mfma_f32_16x16x32_bf16 v[132:135], v[88:91], v[176:179], v[132:135]
	v_mfma_f32_16x16x32_bf16 v[128:131], v[112:115], v[176:179], v[128:131]
	v_mfma_f32_16x16x32_bf16 v[108:111], v[88:91], v[184:187], v[108:111]
	v_mfma_f32_16x16x32_bf16 v[100:103], v[112:115], v[184:187], v[100:103]
	v_mfma_f32_16x16x32_bf16 v[80:83], v[88:91], v[192:195], v[80:83]
	v_mfma_f32_16x16x32_bf16 v[76:79], v[112:115], v[192:195], v[76:79]
	v_mfma_f32_16x16x32_bf16 v[144:147], v[124:127], v[164:167], v[144:147]
	v_mfma_f32_16x16x32_bf16 v[140:143], v[148:151], v[164:167], v[140:143]
	v_mfma_f32_16x16x32_bf16 v[120:123], v[124:127], v[172:175], v[120:123]
	v_mfma_f32_16x16x32_bf16 v[116:119], v[148:151], v[172:175], v[116:119]
	v_mfma_f32_16x16x32_bf16 v[96:99], v[124:127], v[180:183], v[96:99]
	v_mfma_f32_16x16x32_bf16 v[92:95], v[148:151], v[180:183], v[92:95]
	v_mfma_f32_16x16x32_bf16 v[72:75], v[124:127], v[188:191], v[72:75]
	v_mfma_f32_16x16x32_bf16 v[68:71], v[148:151], v[188:191], v[68:71]
	v_mfma_f32_16x16x32_bf16 v[144:147], v[136:139], v[168:171], v[144:147]
	v_mfma_f32_16x16x32_bf16 v[140:143], v[160:163], v[168:171], v[140:143]
	v_mfma_f32_16x16x32_bf16 v[120:123], v[136:139], v[176:179], v[120:123]
	v_mfma_f32_16x16x32_bf16 v[116:119], v[160:163], v[176:179], v[116:119]
	v_mfma_f32_16x16x32_bf16 v[96:99], v[136:139], v[184:187], v[96:99]
	v_mfma_f32_16x16x32_bf16 v[92:95], v[160:163], v[184:187], v[92:95]
	v_mfma_f32_16x16x32_bf16 v[72:75], v[136:139], v[192:195], v[72:75]
	v_mfma_f32_16x16x32_bf16 v[68:71], v[160:163], v[192:195], v[68:71]
	s_setprio 0
	s_barrier
	s_add_i32 s83, s83, s23
	s_mov_b32 m0, s83
	ds_read_b128 v[164:167], v231 offset:16384
	ds_read_b128 v[168:171], v231 offset:17408
	ds_read_b128 v[172:175], v231 offset:18432
	ds_read_b128 v[176:179], v231 offset:19456
	global_load_lds_dwordx4 v2, s[52:53]
	s_add_i32 m0, s83, 0x2000
	s_add_u32 s86, s52, 0x80000
	s_addc_u32 s87, s53, 0
	s_add_i32 s83, s85, s23
	global_load_lds_dwordx4 v208, s[52:53]
	s_mov_b32 m0, s83
	ds_read_b128 v[192:195], v231 offset:23552
	global_load_lds_dwordx4 v2, s[86:87]
	s_add_i32 m0, s83, 0x2000
	ds_read_b128 v[188:191], v231 offset:22528
	global_load_lds_dwordx4 v208, s[86:87]
	s_add_u32 s98, s54, 0x80
	s_addc_u32 s99, s55, 0
	s_mov_b32 m0, s26
	ds_read_b128 v[184:187], v231 offset:21504
	global_load_lds_dwordx4 v204, s[54:55]
	s_mov_b32 m0, s27
	ds_read_b128 v[180:183], v231 offset:20480
	global_load_lds_dwordx4 v206, s[54:55]
	s_waitcnt vmcnt(8) lgkmcnt(0)
	s_barrier
	s_setprio 1
	v_mfma_f32_16x16x32_bf16 v[64:67], v[84:87], v[164:167], v[64:67]
	v_mfma_f32_16x16x32_bf16 v[60:63], v[104:107], v[164:167], v[60:63]
	v_mfma_f32_16x16x32_bf16 v[48:51], v[84:87], v[172:175], v[48:51]
	v_mfma_f32_16x16x32_bf16 v[44:47], v[104:107], v[172:175], v[44:47]
	v_mfma_f32_16x16x32_bf16 v[32:35], v[84:87], v[180:183], v[32:35]
	v_mfma_f32_16x16x32_bf16 v[28:31], v[104:107], v[180:183], v[28:31]
	v_mfma_f32_16x16x32_bf16 v[16:19], v[84:87], v[188:191], v[16:19]
	v_mfma_f32_16x16x32_bf16 v[12:15], v[104:107], v[188:191], v[12:15]
	v_mfma_f32_16x16x32_bf16 v[64:67], v[88:91], v[168:171], v[64:67]
	v_mfma_f32_16x16x32_bf16 v[60:63], v[112:115], v[168:171], v[60:63]
	v_mfma_f32_16x16x32_bf16 v[48:51], v[88:91], v[176:179], v[48:51]
	v_mfma_f32_16x16x32_bf16 v[44:47], v[112:115], v[176:179], v[44:47]
	v_mfma_f32_16x16x32_bf16 v[32:35], v[88:91], v[184:187], v[32:35]
	v_mfma_f32_16x16x32_bf16 v[28:31], v[112:115], v[184:187], v[28:31]
	v_mfma_f32_16x16x32_bf16 v[16:19], v[88:91], v[192:195], v[16:19]
	v_mfma_f32_16x16x32_bf16 v[12:15], v[112:115], v[192:195], v[12:15]
	v_mfma_f32_16x16x32_bf16 v[56:59], v[124:127], v[164:167], v[56:59]
	v_mfma_f32_16x16x32_bf16 v[52:55], v[148:151], v[164:167], v[52:55]
	v_mfma_f32_16x16x32_bf16 v[40:43], v[124:127], v[172:175], v[40:43]
	v_mfma_f32_16x16x32_bf16 v[36:39], v[148:151], v[172:175], v[36:39]
	v_mfma_f32_16x16x32_bf16 v[24:27], v[124:127], v[180:183], v[24:27]
	v_mfma_f32_16x16x32_bf16 v[20:23], v[148:151], v[180:183], v[20:23]
	v_mfma_f32_16x16x32_bf16 v[8:11], v[124:127], v[188:191], v[8:11]
	v_mfma_f32_16x16x32_bf16 v[4:7], v[148:151], v[188:191], v[4:7]
	v_mfma_f32_16x16x32_bf16 v[56:59], v[136:139], v[168:171], v[56:59]
	v_mfma_f32_16x16x32_bf16 v[52:55], v[160:163], v[168:171], v[52:55]
	v_mfma_f32_16x16x32_bf16 v[40:43], v[136:139], v[176:179], v[40:43]
	v_mfma_f32_16x16x32_bf16 v[36:39], v[160:163], v[176:179], v[36:39]
	v_mfma_f32_16x16x32_bf16 v[24:27], v[136:139], v[184:187], v[24:27]
	v_mfma_f32_16x16x32_bf16 v[20:23], v[160:163], v[184:187], v[20:23]
	v_mfma_f32_16x16x32_bf16 v[8:11], v[136:139], v[192:195], v[8:11]
	v_mfma_f32_16x16x32_bf16 v[4:7], v[160:163], v[192:195], v[4:7]
	s_setprio 0
	s_barrier
; #define PG8_STAGE(bufoff, gbase, voff) do { _Pragma("unroll") for (int _i = 0; _i < 2; ++_i) \
;         __builtin_amdgcn_global_load_lds((const unsigned*)((const char*)(gbase) + (voff)[_i]), (LAS unsigned*)(lds + (bufoff) + ldsw + _i * 8192), 16, 0, 0); } while (0)
; #define PG8_LDA(dst, b, h) do { _Pragma("unroll") for (int m = 0; m < 4; ++m) _Pragma("unroll") for (int k = 0; k < 2; ++k) dst[m][k] = *(const LAS bf16x8*)(lds + PG8_SA(b, h) + aoff + m * 2048 + k * 1024); } while (0)
; #define PG8_LDB(dst, b, h) do { _Pragma("unroll") for (int n = 0; n < 2; ++n) _Pragma("unroll") for (int k = 0; k < 2; ++k) dst[n][k] = *(const LAS bf16x8*)(lds + PG8_SB(b, h) + boff + n * 2048 + k * 1024); } while (0)
; #define PG8_MMA(ai, bj, At, Bt) do { __builtin_amdgcn_s_setprio(1); _Pragma("unroll") for (int m = 0; m < 4; ++m) _Pragma("unroll") for (int n = 0; n < 2; ++n) _Pragma("unroll") for (int k = 0; k < 2; ++k) \
;         acc[ai][bj][m][n] = __builtin_amdgcn_mfma_f32_16x16x32_bf16(Bt[n][k], At[m][k], acc[ai][bj][m][n], 0, 0, 0); __builtin_amdgcn_s_setprio(0); } while (0)
; #define PG8_WAIT_V(n) asm volatile("s_waitcnt vmcnt(" #n ")" ::: "memory")
; #define PG8_WAIT_L(n) asm volatile("s_waitcnt lgkmcnt(" #n ")" ::: "memory")
; #define PG8_BAR __builtin_amdgcn_s_barrier()
; #define PG8_SCHED __builtin_amdgcn_sched_barrier(0)
; template <class Epi, class Sched>
; DI void gemm_phase(LAS unsigned char* lds, const Sched& S, const Epi& E) {
;     ...
;             PG8_LDB(B0, 1, 0); PG8_LDB(B1, 1, 1); PG8_SCHED; PG8_LDA(At, 1, 0); PG8_STAGE(PG8_SA(0, 1), a2 + hstepA, voffA);
;             PG8_WAIT_V(8); PG8_WAIT_L(0); PG8_BAR; PG8_MMA(0, 0, At, B0); PG8_MMA(0, 1, At, B1); PG8_BAR; PG8_SCHED;
;             PG8_LDA(At, 1, 1); PG8_STAGE(PG8_SB(1, 0), b3, voffB); PG8_STAGE(PG8_SB(1, 1), b3 + hstepB, voffB); PG8_STAGE(PG8_SA(1, 0), a3, voffA);
;             PG8_WAIT_V(8); PG8_WAIT_L(0); PG8_BAR; PG8_MMA(1, 0, At, B0); PG8_MMA(1, 1, At, B1); PG8_BAR; PG8_SCHED;
;         }
;         if (wr == 0) PG8_BAR;
	s_add_i32 s83, 0, 0x18000
	s_add_i32 s85, 0, 0x1c000
	ds_read_b128 v[84:87], v214 offset:32768
	ds_read_b128 v[88:91], v214 offset:33792
	ds_read_b128 v[104:107], v214 offset:34816
	ds_read_b128 v[112:115], v214 offset:35840
	ds_read_b128 v[124:127], v214 offset:49152
	ds_read_b128 v[136:139], v214 offset:50176
	ds_read_b128 v[148:151], v214 offset:51200
	ds_read_b128 v[160:163], v214 offset:52224
	s_add_u32 s54, s54, 0x80000
	s_addc_u32 s55, s55, 0
	s_mov_b32 m0, s60
	ds_read_b128 v[164:167], v231 offset:32768
	ds_read_b128 v[168:171], v231 offset:33792
	ds_read_b128 v[172:175], v231 offset:34816
	ds_read_b128 v[176:179], v231 offset:35840
	ds_read_b128 v[180:183], v231 offset:36864
	ds_read_b128 v[184:187], v231 offset:37888
	ds_read_b128 v[188:191], v231 offset:38912
	global_load_lds_dwordx4 v204, s[54:55]
	s_mov_b32 m0, s61
	ds_read_b128 v[192:195], v231 offset:39936
	global_load_lds_dwordx4 v206, s[54:55]
	s_waitcnt vmcnt(8) lgkmcnt(0)
	s_barrier
	s_setprio 1
	v_mfma_f32_16x16x32_bf16 v[156:159], v[84:87], v[164:167], v[156:159]
	v_mfma_f32_16x16x32_bf16 v[152:155], v[104:107], v[164:167], v[152:155]
	v_mfma_f32_16x16x32_bf16 v[132:135], v[84:87], v[172:175], v[132:135]
	v_mfma_f32_16x16x32_bf16 v[128:131], v[104:107], v[172:175], v[128:131]
	v_mfma_f32_16x16x32_bf16 v[108:111], v[84:87], v[180:183], v[108:111]
	v_mfma_f32_16x16x32_bf16 v[100:103], v[104:107], v[180:183], v[100:103]
	v_mfma_f32_16x16x32_bf16 v[80:83], v[84:87], v[188:191], v[80:83]
	v_mfma_f32_16x16x32_bf16 v[76:79], v[104:107], v[188:191], v[76:79]
	v_mfma_f32_16x16x32_bf16 v[156:159], v[88:91], v[168:171], v[156:159]
	v_mfma_f32_16x16x32_bf16 v[152:155], v[112:115], v[168:171], v[152:155]
	v_mfma_f32_16x16x32_bf16 v[132:135], v[88:91], v[176:179], v[132:135]
	v_mfma_f32_16x16x32_bf16 v[128:131], v[112:115], v[176:179], v[128:131]
	v_mfma_f32_16x16x32_bf16 v[108:111], v[88:91], v[184:187], v[108:111]
	v_mfma_f32_16x16x32_bf16 v[100:103], v[112:115], v[184:187], v[100:103]
	v_mfma_f32_16x16x32_bf16 v[80:83], v[88:91], v[192:195], v[80:83]
	v_mfma_f32_16x16x32_bf16 v[76:79], v[112:115], v[192:195], v[76:79]
	v_mfma_f32_16x16x32_bf16 v[144:147], v[124:127], v[164:167], v[144:147]
	v_mfma_f32_16x16x32_bf16 v[140:143], v[148:151], v[164:167], v[140:143]
	v_mfma_f32_16x16x32_bf16 v[120:123], v[124:127], v[172:175], v[120:123]
	v_mfma_f32_16x16x32_bf16 v[116:119], v[148:151], v[172:175], v[116:119]
	v_mfma_f32_16x16x32_bf16 v[96:99], v[124:127], v[180:183], v[96:99]
	v_mfma_f32_16x16x32_bf16 v[92:95], v[148:151], v[180:183], v[92:95]
	v_mfma_f32_16x16x32_bf16 v[72:75], v[124:127], v[188:191], v[72:75]
	v_mfma_f32_16x16x32_bf16 v[68:71], v[148:151], v[188:191], v[68:71]
	v_mfma_f32_16x16x32_bf16 v[144:147], v[136:139], v[168:171], v[144:147]
	v_mfma_f32_16x16x32_bf16 v[140:143], v[160:163], v[168:171], v[140:143]
	v_mfma_f32_16x16x32_bf16 v[120:123], v[136:139], v[176:179], v[120:123]
	v_mfma_f32_16x16x32_bf16 v[116:119], v[160:163], v[176:179], v[116:119]
	v_mfma_f32_16x16x32_bf16 v[96:99], v[136:139], v[184:187], v[96:99]
	v_mfma_f32_16x16x32_bf16 v[92:95], v[160:163], v[184:187], v[92:95]
	v_mfma_f32_16x16x32_bf16 v[72:75], v[136:139], v[192:195], v[72:75]
	v_mfma_f32_16x16x32_bf16 v[68:71], v[160:163], v[192:195], v[68:71]
	s_setprio 0
	s_barrier
	s_add_i32 s54, s83, s23
	s_add_u32 s52, s52, 0x80
	s_addc_u32 s53, s53, 0
	s_mov_b32 m0, s54
	ds_read_b128 v[164:167], v231 offset:49152
	ds_read_b128 v[168:171], v231 offset:50176
	ds_read_b128 v[172:175], v231 offset:51200
	ds_read_b128 v[176:179], v231 offset:52224
	global_load_lds_dwordx4 v2, s[52:53]
	s_add_i32 m0, s54, 0x2000
	s_add_i32 s54, s85, s23
	global_load_lds_dwordx4 v208, s[52:53]
	s_add_u32 s52, s52, 0x80000
	s_addc_u32 s53, s53, 0
	s_mov_b32 m0, s54
	ds_read_b128 v[192:195], v231 offset:56320
	global_load_lds_dwordx4 v2, s[52:53]
	s_add_i32 m0, s54, 0x2000
	ds_read_b128 v[188:191], v231 offset:55296
	global_load_lds_dwordx4 v208, s[52:53]
	s_mov_b32 m0, s71
	ds_read_b128 v[184:187], v231 offset:54272
	global_load_lds_dwordx4 v204, s[98:99]
	s_mov_b32 m0, s72
	ds_read_b128 v[180:183], v231 offset:53248
	global_load_lds_dwordx4 v206, s[98:99]
	s_waitcnt vmcnt(8) lgkmcnt(0)
	s_barrier
	s_setprio 1
	v_mfma_f32_16x16x32_bf16 v[64:67], v[84:87], v[164:167], v[64:67]
	v_mfma_f32_16x16x32_bf16 v[60:63], v[104:107], v[164:167], v[60:63]
	v_mfma_f32_16x16x32_bf16 v[48:51], v[84:87], v[172:175], v[48:51]
	v_mfma_f32_16x16x32_bf16 v[44:47], v[104:107], v[172:175], v[44:47]
	v_mfma_f32_16x16x32_bf16 v[32:35], v[84:87], v[180:183], v[32:35]
	v_mfma_f32_16x16x32_bf16 v[28:31], v[104:107], v[180:183], v[28:31]
	v_mfma_f32_16x16x32_bf16 v[16:19], v[84:87], v[188:191], v[16:19]
	v_mfma_f32_16x16x32_bf16 v[12:15], v[104:107], v[188:191], v[12:15]
	v_mfma_f32_16x16x32_bf16 v[64:67], v[88:91], v[168:171], v[64:67]
	v_mfma_f32_16x16x32_bf16 v[60:63], v[112:115], v[168:171], v[60:63]
	v_mfma_f32_16x16x32_bf16 v[48:51], v[88:91], v[176:179], v[48:51]
	v_mfma_f32_16x16x32_bf16 v[44:47], v[112:115], v[176:179], v[44:47]
	v_mfma_f32_16x16x32_bf16 v[32:35], v[88:91], v[184:187], v[32:35]
	v_mfma_f32_16x16x32_bf16 v[28:31], v[112:115], v[184:187], v[28:31]
	v_mfma_f32_16x16x32_bf16 v[16:19], v[88:91], v[192:195], v[16:19]
	v_mfma_f32_16x16x32_bf16 v[12:15], v[112:115], v[192:195], v[12:15]
	v_mfma_f32_16x16x32_bf16 v[56:59], v[124:127], v[164:167], v[56:59]
	v_mfma_f32_16x16x32_bf16 v[52:55], v[148:151], v[164:167], v[52:55]
	v_mfma_f32_16x16x32_bf16 v[40:43], v[124:127], v[172:175], v[40:43]
	v_mfma_f32_16x16x32_bf16 v[36:39], v[148:151], v[172:175], v[36:39]
	v_mfma_f32_16x16x32_bf16 v[24:27], v[124:127], v[180:183], v[24:27]
	v_mfma_f32_16x16x32_bf16 v[20:23], v[148:151], v[180:183], v[20:23]
	v_mfma_f32_16x16x32_bf16 v[8:11], v[124:127], v[188:191], v[8:11]
	v_mfma_f32_16x16x32_bf16 v[4:7], v[148:151], v[188:191], v[4:7]
	v_mfma_f32_16x16x32_bf16 v[56:59], v[136:139], v[168:171], v[56:59]
	v_mfma_f32_16x16x32_bf16 v[52:55], v[160:163], v[168:171], v[52:55]
	v_mfma_f32_16x16x32_bf16 v[40:43], v[136:139], v[176:179], v[40:43]
	v_mfma_f32_16x16x32_bf16 v[36:39], v[160:163], v[176:179], v[36:39]
	v_mfma_f32_16x16x32_bf16 v[24:27], v[136:139], v[184:187], v[24:27]
	v_mfma_f32_16x16x32_bf16 v[20:23], v[160:163], v[184:187], v[20:23]
	v_mfma_f32_16x16x32_bf16 v[8:11], v[136:139], v[192:195], v[8:11]
	v_mfma_f32_16x16x32_bf16 v[4:7], v[160:163], v[192:195], v[4:7]
	s_setprio 0
	s_barrier
	s_add_u32 s80, s80, 0x100
	s_addc_u32 s81, s81, 0
	s_add_u32 s42, s42, 0x100
	s_addc_u32 s43, s43, 0
	s_cmp_ge_i32 s82, s75
	s_mov_b32 s52, s82
	s_cbranch_scc0 .LBB0_1104
	s_and_b64 vcc, exec, s[38:39]
	s_cbranch_vccz .LBB0_1107
	s_barrier

; #define PG8_STAGE(bufoff, gbase, voff) do { _Pragma("unroll") for (int _i = 0; _i < 2; ++_i) \
;         __builtin_amdgcn_global_load_lds((const unsigned*)((const char*)(gbase) + (voff)[_i]), (LAS unsigned*)(lds + (bufoff) + ldsw + _i * 8192), 16, 0, 0); } while (0)
; #define PG8_LDA(dst, b, h) do { _Pragma("unroll") for (int m = 0; m < 4; ++m) _Pragma("unroll") for (int k = 0; k < 2; ++k) dst[m][k] = *(const LAS bf16x8*)(lds + PG8_SA(b, h) + aoff + m * 2048 + k * 1024); } while (0)
; #define PG8_LDB(dst, b, h) do { _Pragma("unroll") for (int n = 0; n < 2; ++n) _Pragma("unroll") for (int k = 0; k < 2; ++k) dst[n][k] = *(const LAS bf16x8*)(lds + PG8_SB(b, h) + boff + n * 2048 + k * 1024); } while (0)
; #define PG8_MMA(ai, bj, At, Bt) do { __builtin_amdgcn_s_setprio(1); _Pragma("unroll") for (int m = 0; m < 4; ++m) _Pragma("unroll") for (int n = 0; n < 2; ++n) _Pragma("unroll") for (int k = 0; k < 2; ++k) \
;         acc[ai][bj][m][n] = __builtin_amdgcn_mfma_f32_16x16x32_bf16(Bt[n][k], At[m][k], acc[ai][bj][m][n], 0, 0, 0); __builtin_amdgcn_s_setprio(0); } while (0)
; #define PG8_WAIT_V(n) asm volatile("s_waitcnt vmcnt(" #n ")" ::: "memory")
; #define PG8_WAIT_L(n) asm volatile("s_waitcnt lgkmcnt(" #n ")" ::: "memory")
; #define PG8_BAR __builtin_amdgcn_s_barrier()
; template <class Epi, class Sched>
; DI void gemm_phase(LAS unsigned char* lds, const Sched& S, const Epi& E) {
;     ...
;         for (int t = 0; t < nt; t += 2) {
;             const bool last = (t == nt - 2);
;             const char* a1 = cA + (size_t)(t + 1) * kstep;
;             const char* a2 = last ? nA : cA + (size_t)(t + 2) * kstep; const char* b2 = last ? nB : cB + (size_t)(t + 2) * kstep;
;             const char* a3 = a2 + kstep; const char* b3 = b2 + kstep;
;             if constexpr (Epi::HOOK) { if (cur.ks < 0 && (t == 16 || t == 32)) E.hook(acc, cur, t >> 4, wr, wc, fr, fq); }
;             PG8_LDB(B0, 0, 0); PG8_LDB(B1, 0, 1); PG8_SCHED; PG8_LDA(At, 0, 0); PG8_STAGE(PG8_SA(1, 1), a1 + hstepA, voffA);
;             PG8_WAIT_V(8); PG8_WAIT_L(0); PG8_BAR; PG8_MMA(0, 0, At, B0); PG8_MMA(0, 1, At, B1); PG8_BAR; PG8_SCHED;
;             PG8_LDA(At, 0, 1); PG8_STAGE(PG8_SB(0, 0), b2, voffB); PG8_STAGE(PG8_SB(0, 1), b2 + hstepB, voffB); PG8_STAGE(PG8_SA(0, 0), a2, voffA);
;             PG8_WAIT_V(8); PG8_WAIT_L(0); PG8_BAR; PG8_MMA(1, 0, At, B0); PG8_MMA(1, 1, At, B1); PG8_BAR; PG8_SCHED;
.LBB0_1184:
	v_add_u32_e32 v194, 0x10000, v146
	s_add_i32 s85, s54, 2
	s_add_u32 s55, s42, 0xfff80080
	s_addc_u32 s56, s43, -1
	s_add_i32 s86, 0, 0x10000
	s_cmp_eq_u32 s81, s54
	s_cselect_b32 s57, s58, s56
	s_cselect_b32 s56, s59, s55
	s_cselect_b32 s55, s60, s83
	s_cselect_b32 s54, s61, s82
	s_add_i32 s88, 0, 0x14000
	ds_read_b128 v[142:145], v194
	ds_read_b128 v[150:153], v194 offset:1024
	ds_read_b128 v[154:157], v194 offset:2048
	ds_read_b128 v[158:161], v194 offset:3072
	ds_read_b128 v[162:165], v194 offset:16384
	ds_read_b128 v[166:169], v194 offset:17408
	ds_read_b128 v[170:173], v194 offset:18432
	ds_read_b128 v[174:177], v194 offset:19456
	s_add_i32 m0, s26, 0xc000
	ds_read_b128 v[178:181], v148
	ds_read_b128 v[182:185], v148 offset:1024
	ds_read_b128 v[186:189], v148 offset:2048
	ds_read_b128 v[190:193], v148 offset:3072
	ds_read_b128 v[204:207], v148 offset:4096
	ds_read_b128 v[208:211], v148 offset:5120
	ds_read_b128 v[212:215], v148 offset:6144
	global_load_lds_dwordx4 v140, s[42:43]
	s_add_i32 m0, s26, 0xe000
	ds_read_b128 v[230:233], v148 offset:7168
	global_load_lds_dwordx4 v138, s[42:43]
	s_waitcnt vmcnt(8) lgkmcnt(0)
	s_barrier
	s_setprio 1
	v_mfma_f32_16x16x32_bf16 v[128:131], v[142:145], v[178:181], v[128:131]
	v_mfma_f32_16x16x32_bf16 v[124:127], v[154:157], v[178:181], v[124:127]
	v_mfma_f32_16x16x32_bf16 v[112:115], v[142:145], v[186:189], v[112:115]
	v_mfma_f32_16x16x32_bf16 v[108:111], v[154:157], v[186:189], v[108:111]
	v_mfma_f32_16x16x32_bf16 v[96:99], v[142:145], v[204:207], v[96:99]
	v_mfma_f32_16x16x32_bf16 v[92:95], v[154:157], v[204:207], v[92:95]
	v_mfma_f32_16x16x32_bf16 v[80:83], v[142:145], v[212:215], v[80:83]
	v_mfma_f32_16x16x32_bf16 v[76:79], v[154:157], v[212:215], v[76:79]
	v_mfma_f32_16x16x32_bf16 v[128:131], v[150:153], v[182:185], v[128:131]
	v_mfma_f32_16x16x32_bf16 v[124:127], v[158:161], v[182:185], v[124:127]
	v_mfma_f32_16x16x32_bf16 v[112:115], v[150:153], v[190:193], v[112:115]
	v_mfma_f32_16x16x32_bf16 v[108:111], v[158:161], v[190:193], v[108:111]
	v_mfma_f32_16x16x32_bf16 v[96:99], v[150:153], v[208:211], v[96:99]
	v_mfma_f32_16x16x32_bf16 v[92:95], v[158:161], v[208:211], v[92:95]
	v_mfma_f32_16x16x32_bf16 v[80:83], v[150:153], v[230:233], v[80:83]
	v_mfma_f32_16x16x32_bf16 v[76:79], v[158:161], v[230:233], v[76:79]
	v_mfma_f32_16x16x32_bf16 v[120:123], v[162:165], v[178:181], v[120:123]
	v_mfma_f32_16x16x32_bf16 v[116:119], v[170:173], v[178:181], v[116:119]
	v_mfma_f32_16x16x32_bf16 v[104:107], v[162:165], v[186:189], v[104:107]
	v_mfma_f32_16x16x32_bf16 v[100:103], v[170:173], v[186:189], v[100:103]
	v_mfma_f32_16x16x32_bf16 v[88:91], v[162:165], v[204:207], v[88:91]
	v_mfma_f32_16x16x32_bf16 v[84:87], v[170:173], v[204:207], v[84:87]
	v_mfma_f32_16x16x32_bf16 v[72:75], v[162:165], v[212:215], v[72:75]
	v_mfma_f32_16x16x32_bf16 v[68:71], v[170:173], v[212:215], v[68:71]
	v_mfma_f32_16x16x32_bf16 v[120:123], v[166:169], v[182:185], v[120:123]
	v_mfma_f32_16x16x32_bf16 v[116:119], v[174:177], v[182:185], v[116:119]
	v_mfma_f32_16x16x32_bf16 v[104:107], v[166:169], v[190:193], v[104:107]
	v_mfma_f32_16x16x32_bf16 v[100:103], v[174:177], v[190:193], v[100:103]
	v_mfma_f32_16x16x32_bf16 v[88:91], v[166:169], v[208:211], v[88:91]
	v_mfma_f32_16x16x32_bf16 v[84:87], v[174:177], v[208:211], v[84:87]
	v_mfma_f32_16x16x32_bf16 v[72:75], v[166:169], v[230:233], v[72:75]
	v_mfma_f32_16x16x32_bf16 v[68:71], v[174:177], v[230:233], v[68:71]
	s_setprio 0
	s_barrier
	s_add_i32 s86, s86, s23
	s_mov_b32 m0, s86
	ds_read_b128 v[178:181], v148 offset:16384
	ds_read_b128 v[182:185], v148 offset:17408
	ds_read_b128 v[186:189], v148 offset:18432
	ds_read_b128 v[190:193], v148 offset:19456
	global_load_lds_dwordx4 v2, s[54:55]
	s_add_i32 m0, s86, 0x2000
	s_add_u32 s86, s54, 0x80000
	s_addc_u32 s87, s55, 0
	s_add_i32 s88, s88, s23
	global_load_lds_dwordx4 v136, s[54:55]
	s_mov_b32 m0, s88
	ds_read_b128 v[230:233], v148 offset:23552
	global_load_lds_dwordx4 v2, s[86:87]
	s_add_i32 m0, s88, 0x2000
	ds_read_b128 v[212:215], v148 offset:22528
	global_load_lds_dwordx4 v136, s[86:87]
	s_add_u32 s98, s56, 0x80
	s_addc_u32 s99, s57, 0
	s_mov_b32 m0, s26
	ds_read_b128 v[208:211], v148 offset:21504
	global_load_lds_dwordx4 v132, s[56:57]
	s_mov_b32 m0, s27
	ds_read_b128 v[204:207], v148 offset:20480
	global_load_lds_dwordx4 v134, s[56:57]
	s_waitcnt vmcnt(8) lgkmcnt(0)
	s_barrier
	s_setprio 1
	v_mfma_f32_16x16x32_bf16 v[64:67], v[142:145], v[178:181], v[64:67]
	v_mfma_f32_16x16x32_bf16 v[60:63], v[154:157], v[178:181], v[60:63]
	v_mfma_f32_16x16x32_bf16 v[48:51], v[142:145], v[186:189], v[48:51]
	v_mfma_f32_16x16x32_bf16 v[44:47], v[154:157], v[186:189], v[44:47]
	v_mfma_f32_16x16x32_bf16 v[32:35], v[142:145], v[204:207], v[32:35]
	v_mfma_f32_16x16x32_bf16 v[28:31], v[154:157], v[204:207], v[28:31]
	v_mfma_f32_16x16x32_bf16 v[16:19], v[142:145], v[212:215], v[16:19]
	v_mfma_f32_16x16x32_bf16 v[12:15], v[154:157], v[212:215], v[12:15]
	v_mfma_f32_16x16x32_bf16 v[64:67], v[150:153], v[182:185], v[64:67]
	v_mfma_f32_16x16x32_bf16 v[60:63], v[158:161], v[182:185], v[60:63]
	v_mfma_f32_16x16x32_bf16 v[48:51], v[150:153], v[190:193], v[48:51]
	v_mfma_f32_16x16x32_bf16 v[44:47], v[158:161], v[190:193], v[44:47]
	v_mfma_f32_16x16x32_bf16 v[32:35], v[150:153], v[208:211], v[32:35]
	v_mfma_f32_16x16x32_bf16 v[28:31], v[158:161], v[208:211], v[28:31]
	v_mfma_f32_16x16x32_bf16 v[16:19], v[150:153], v[230:233], v[16:19]
	v_mfma_f32_16x16x32_bf16 v[12:15], v[158:161], v[230:233], v[12:15]
	v_mfma_f32_16x16x32_bf16 v[56:59], v[162:165], v[178:181], v[56:59]
	v_mfma_f32_16x16x32_bf16 v[52:55], v[170:173], v[178:181], v[52:55]
	v_mfma_f32_16x16x32_bf16 v[40:43], v[162:165], v[186:189], v[40:43]
	v_mfma_f32_16x16x32_bf16 v[36:39], v[170:173], v[186:189], v[36:39]
	v_mfma_f32_16x16x32_bf16 v[24:27], v[162:165], v[204:207], v[24:27]
	v_mfma_f32_16x16x32_bf16 v[20:23], v[170:173], v[204:207], v[20:23]
	v_mfma_f32_16x16x32_bf16 v[8:11], v[162:165], v[212:215], v[8:11]
	v_mfma_f32_16x16x32_bf16 v[4:7], v[170:173], v[212:215], v[4:7]
	v_mfma_f32_16x16x32_bf16 v[56:59], v[166:169], v[182:185], v[56:59]
	v_mfma_f32_16x16x32_bf16 v[52:55], v[174:177], v[182:185], v[52:55]
	v_mfma_f32_16x16x32_bf16 v[40:43], v[166:169], v[190:193], v[40:43]
	v_mfma_f32_16x16x32_bf16 v[36:39], v[174:177], v[190:193], v[36:39]
	v_mfma_f32_16x16x32_bf16 v[24:27], v[166:169], v[208:211], v[24:27]
	v_mfma_f32_16x16x32_bf16 v[20:23], v[174:177], v[208:211], v[20:23]
	v_mfma_f32_16x16x32_bf16 v[8:11], v[166:169], v[230:233], v[8:11]
	v_mfma_f32_16x16x32_bf16 v[4:7], v[174:177], v[230:233], v[4:7]
	s_setprio 0
	s_barrier
; #define PG8_STAGE(bufoff, gbase, voff) do { _Pragma("unroll") for (int _i = 0; _i < 2; ++_i) \
;         __builtin_amdgcn_global_load_lds((const unsigned*)((const char*)(gbase) + (voff)[_i]), (LAS unsigned*)(lds + (bufoff) + ldsw + _i * 8192), 16, 0, 0); } while (0)
; #define PG8_LDA(dst, b, h) do { _Pragma("unroll") for (int m = 0; m < 4; ++m) _Pragma("unroll") for (int k = 0; k < 2; ++k) dst[m][k] = *(const LAS bf16x8*)(lds + PG8_SA(b, h) + aoff + m * 2048 + k * 1024); } while (0)
; #define PG8_LDB(dst, b, h) do { _Pragma("unroll") for (int n = 0; n < 2; ++n) _Pragma("unroll") for (int k = 0; k < 2; ++k) dst[n][k] = *(const LAS bf16x8*)(lds + PG8_SB(b, h) + boff + n * 2048 + k * 1024); } while (0)
; #define PG8_MMA(ai, bj, At, Bt) do { __builtin_amdgcn_s_setprio(1); _Pragma("unroll") for (int m = 0; m < 4; ++m) _Pragma("unroll") for (int n = 0; n < 2; ++n) _Pragma("unroll") for (int k = 0; k < 2; ++k) \
;         acc[ai][bj][m][n] = __builtin_amdgcn_mfma_f32_16x16x32_bf16(Bt[n][k], At[m][k], acc[ai][bj][m][n], 0, 0, 0); __builtin_amdgcn_s_setprio(0); } while (0)
; #define PG8_WAIT_V(n) asm volatile("s_waitcnt vmcnt(" #n ")" ::: "memory")
; #define PG8_WAIT_L(n) asm volatile("s_waitcnt lgkmcnt(" #n ")" ::: "memory")
; #define PG8_BAR __builtin_amdgcn_s_barrier()
; #define PG8_SCHED __builtin_amdgcn_sched_barrier(0)
; template <class Epi, class Sched>
; DI void gemm_phase(LAS unsigned char* lds, const Sched& S, const Epi& E) {
;     ...
;             PG8_LDB(B0, 1, 0); PG8_LDB(B1, 1, 1); PG8_SCHED; PG8_LDA(At, 1, 0); PG8_STAGE(PG8_SA(0, 1), a2 + hstepA, voffA);
;             PG8_WAIT_V(8); PG8_WAIT_L(0); PG8_BAR; PG8_MMA(0, 0, At, B0); PG8_MMA(0, 1, At, B1); PG8_BAR; PG8_SCHED;
;             PG8_LDA(At, 1, 1); PG8_STAGE(PG8_SB(1, 0), b3, voffB); PG8_STAGE(PG8_SB(1, 1), b3 + hstepB, voffB); PG8_STAGE(PG8_SA(1, 0), a3, voffA);
;             PG8_WAIT_V(8); PG8_WAIT_L(0); PG8_BAR; PG8_MMA(1, 0, At, B0); PG8_MMA(1, 1, At, B1); PG8_BAR; PG8_SCHED;
;         }
;         if (wr == 0) PG8_BAR;
	s_add_i32 s86, 0, 0x18000
	s_add_i32 s87, 0, 0x1c000
	ds_read_b128 v[142:145], v194 offset:32768
	ds_read_b128 v[150:153], v194 offset:33792
	ds_read_b128 v[154:157], v194 offset:34816
	ds_read_b128 v[158:161], v194 offset:35840
	ds_read_b128 v[162:165], v194 offset:49152
	ds_read_b128 v[166:169], v194 offset:50176
	ds_read_b128 v[170:173], v194 offset:51200
	ds_read_b128 v[174:177], v194 offset:52224
	s_add_u32 s56, s56, 0x80000
	s_addc_u32 s57, s57, 0
	s_mov_b32 m0, s65
	ds_read_b128 v[178:181], v148 offset:32768
	ds_read_b128 v[182:185], v148 offset:33792
	ds_read_b128 v[186:189], v148 offset:34816
	ds_read_b128 v[190:193], v148 offset:35840
	ds_read_b128 v[204:207], v148 offset:36864
	ds_read_b128 v[208:211], v148 offset:37888
	ds_read_b128 v[212:215], v148 offset:38912
	global_load_lds_dwordx4 v132, s[56:57]
	s_mov_b32 m0, s66
	ds_read_b128 v[230:233], v148 offset:39936
	global_load_lds_dwordx4 v134, s[56:57]
	s_waitcnt vmcnt(8) lgkmcnt(0)
	s_barrier
	s_setprio 1
	v_mfma_f32_16x16x32_bf16 v[128:131], v[142:145], v[178:181], v[128:131]
	v_mfma_f32_16x16x32_bf16 v[124:127], v[154:157], v[178:181], v[124:127]
	v_mfma_f32_16x16x32_bf16 v[112:115], v[142:145], v[186:189], v[112:115]
	v_mfma_f32_16x16x32_bf16 v[108:111], v[154:157], v[186:189], v[108:111]
	v_mfma_f32_16x16x32_bf16 v[96:99], v[142:145], v[204:207], v[96:99]
	v_mfma_f32_16x16x32_bf16 v[92:95], v[154:157], v[204:207], v[92:95]
	v_mfma_f32_16x16x32_bf16 v[80:83], v[142:145], v[212:215], v[80:83]
	v_mfma_f32_16x16x32_bf16 v[76:79], v[154:157], v[212:215], v[76:79]
	v_mfma_f32_16x16x32_bf16 v[128:131], v[150:153], v[182:185], v[128:131]
	v_mfma_f32_16x16x32_bf16 v[124:127], v[158:161], v[182:185], v[124:127]
	v_mfma_f32_16x16x32_bf16 v[112:115], v[150:153], v[190:193], v[112:115]
	v_mfma_f32_16x16x32_bf16 v[108:111], v[158:161], v[190:193], v[108:111]
	v_mfma_f32_16x16x32_bf16 v[96:99], v[150:153], v[208:211], v[96:99]
	v_mfma_f32_16x16x32_bf16 v[92:95], v[158:161], v[208:211], v[92:95]
	v_mfma_f32_16x16x32_bf16 v[80:83], v[150:153], v[230:233], v[80:83]
	v_mfma_f32_16x16x32_bf16 v[76:79], v[158:161], v[230:233], v[76:79]
	v_mfma_f32_16x16x32_bf16 v[120:123], v[162:165], v[178:181], v[120:123]
	v_mfma_f32_16x16x32_bf16 v[116:119], v[170:173], v[178:181], v[116:119]
	v_mfma_f32_16x16x32_bf16 v[104:107], v[162:165], v[186:189], v[104:107]
	v_mfma_f32_16x16x32_bf16 v[100:103], v[170:173], v[186:189], v[100:103]
	v_mfma_f32_16x16x32_bf16 v[88:91], v[162:165], v[204:207], v[88:91]
	v_mfma_f32_16x16x32_bf16 v[84:87], v[170:173], v[204:207], v[84:87]
	v_mfma_f32_16x16x32_bf16 v[72:75], v[162:165], v[212:215], v[72:75]
	v_mfma_f32_16x16x32_bf16 v[68:71], v[170:173], v[212:215], v[68:71]
	v_mfma_f32_16x16x32_bf16 v[120:123], v[166:169], v[182:185], v[120:123]
	v_mfma_f32_16x16x32_bf16 v[116:119], v[174:177], v[182:185], v[116:119]
	v_mfma_f32_16x16x32_bf16 v[104:107], v[166:169], v[190:193], v[104:107]
	v_mfma_f32_16x16x32_bf16 v[100:103], v[174:177], v[190:193], v[100:103]
	v_mfma_f32_16x16x32_bf16 v[88:91], v[166:169], v[208:211], v[88:91]
	v_mfma_f32_16x16x32_bf16 v[84:87], v[174:177], v[208:211], v[84:87]
	v_mfma_f32_16x16x32_bf16 v[72:75], v[166:169], v[230:233], v[72:75]
	v_mfma_f32_16x16x32_bf16 v[68:71], v[174:177], v[230:233], v[68:71]
	s_setprio 0
	s_barrier
	s_add_i32 s56, s86, s23
	s_add_u32 s54, s54, 0x80
	s_addc_u32 s55, s55, 0
	s_mov_b32 m0, s56
	ds_read_b128 v[178:181], v148 offset:49152
	ds_read_b128 v[182:185], v148 offset:50176
	ds_read_b128 v[186:189], v148 offset:51200
	ds_read_b128 v[190:193], v148 offset:52224
	global_load_lds_dwordx4 v2, s[54:55]
	s_add_i32 m0, s56, 0x2000
	s_add_i32 s56, s87, s23
	global_load_lds_dwordx4 v136, s[54:55]
	s_add_u32 s54, s54, 0x80000
	s_addc_u32 s55, s55, 0
	s_mov_b32 m0, s56
	ds_read_b128 v[230:233], v148 offset:56320
	global_load_lds_dwordx4 v2, s[54:55]
	s_add_i32 m0, s56, 0x2000
	ds_read_b128 v[212:215], v148 offset:55296
	global_load_lds_dwordx4 v136, s[54:55]
	s_mov_b32 m0, s73
	ds_read_b128 v[208:211], v148 offset:54272
	global_load_lds_dwordx4 v132, s[98:99]
	s_mov_b32 m0, s74
	ds_read_b128 v[204:207], v148 offset:53248
	global_load_lds_dwordx4 v134, s[98:99]
	s_waitcnt vmcnt(8) lgkmcnt(0)
	s_barrier
	s_setprio 1
	v_mfma_f32_16x16x32_bf16 v[64:67], v[142:145], v[178:181], v[64:67]
	v_mfma_f32_16x16x32_bf16 v[60:63], v[154:157], v[178:181], v[60:63]
	v_mfma_f32_16x16x32_bf16 v[48:51], v[142:145], v[186:189], v[48:51]
	v_mfma_f32_16x16x32_bf16 v[44:47], v[154:157], v[186:189], v[44:47]
	v_mfma_f32_16x16x32_bf16 v[32:35], v[142:145], v[204:207], v[32:35]
	v_mfma_f32_16x16x32_bf16 v[28:31], v[154:157], v[204:207], v[28:31]
	v_mfma_f32_16x16x32_bf16 v[16:19], v[142:145], v[212:215], v[16:19]
	v_mfma_f32_16x16x32_bf16 v[12:15], v[154:157], v[212:215], v[12:15]
	v_mfma_f32_16x16x32_bf16 v[64:67], v[150:153], v[182:185], v[64:67]
	v_mfma_f32_16x16x32_bf16 v[60:63], v[158:161], v[182:185], v[60:63]
	v_mfma_f32_16x16x32_bf16 v[48:51], v[150:153], v[190:193], v[48:51]
	v_mfma_f32_16x16x32_bf16 v[44:47], v[158:161], v[190:193], v[44:47]
	v_mfma_f32_16x16x32_bf16 v[32:35], v[150:153], v[208:211], v[32:35]
	v_mfma_f32_16x16x32_bf16 v[28:31], v[158:161], v[208:211], v[28:31]
	v_mfma_f32_16x16x32_bf16 v[16:19], v[150:153], v[230:233], v[16:19]
	v_mfma_f32_16x16x32_bf16 v[12:15], v[158:161], v[230:233], v[12:15]
	v_mfma_f32_16x16x32_bf16 v[56:59], v[162:165], v[178:181], v[56:59]
	v_mfma_f32_16x16x32_bf16 v[52:55], v[170:173], v[178:181], v[52:55]
	v_mfma_f32_16x16x32_bf16 v[40:43], v[162:165], v[186:189], v[40:43]
	v_mfma_f32_16x16x32_bf16 v[36:39], v[170:173], v[186:189], v[36:39]
	v_mfma_f32_16x16x32_bf16 v[24:27], v[162:165], v[204:207], v[24:27]
	v_mfma_f32_16x16x32_bf16 v[20:23], v[170:173], v[204:207], v[20:23]
	v_mfma_f32_16x16x32_bf16 v[8:11], v[162:165], v[212:215], v[8:11]
	v_mfma_f32_16x16x32_bf16 v[4:7], v[170:173], v[212:215], v[4:7]
	v_mfma_f32_16x16x32_bf16 v[56:59], v[166:169], v[182:185], v[56:59]
	v_mfma_f32_16x16x32_bf16 v[52:55], v[174:177], v[182:185], v[52:55]
	v_mfma_f32_16x16x32_bf16 v[40:43], v[166:169], v[190:193], v[40:43]
	v_mfma_f32_16x16x32_bf16 v[36:39], v[174:177], v[190:193], v[36:39]
	v_mfma_f32_16x16x32_bf16 v[24:27], v[166:169], v[208:211], v[24:27]
	v_mfma_f32_16x16x32_bf16 v[20:23], v[174:177], v[208:211], v[20:23]
	v_mfma_f32_16x16x32_bf16 v[8:11], v[166:169], v[230:233], v[8:11]
	v_mfma_f32_16x16x32_bf16 v[4:7], v[174:177], v[230:233], v[4:7]
	s_setprio 0
	s_barrier
	s_add_u32 s82, s82, 0x100
	s_addc_u32 s83, s83, 0
	s_add_u32 s42, s42, 0x100
	s_addc_u32 s43, s43, 0
	s_cmp_ge_i32 s85, s79
	s_mov_b32 s54, s85
	s_cbranch_scc0 .LBB0_1184
	s_and_b64 vcc, exec, s[8:9]
	s_cbranch_vccz .LBB0_1187
	s_barrier

; #define PG8_STAGE(bufoff, gbase, voff) do { _Pragma("unroll") for (int _i = 0; _i < 2; ++_i) \
;         __builtin_amdgcn_global_load_lds((const unsigned*)((const char*)(gbase) + (voff)[_i]), (LAS unsigned*)(lds + (bufoff) + ldsw + _i * 8192), 16, 0, 0); } while (0)
; #define PG8_LDA(dst, b, h) do { _Pragma("unroll") for (int m = 0; m < 4; ++m) _Pragma("unroll") for (int k = 0; k < 2; ++k) dst[m][k] = *(const LAS bf16x8*)(lds + PG8_SA(b, h) + aoff + m * 2048 + k * 1024); } while (0)
; #define PG8_LDB(dst, b, h) do { _Pragma("unroll") for (int n = 0; n < 2; ++n) _Pragma("unroll") for (int k = 0; k < 2; ++k) dst[n][k] = *(const LAS bf16x8*)(lds + PG8_SB(b, h) + boff + n * 2048 + k * 1024); } while (0)
; #define PG8_MMA(ai, bj, At, Bt) do { __builtin_amdgcn_s_setprio(1); _Pragma("unroll") for (int m = 0; m < 4; ++m) _Pragma("unroll") for (int n = 0; n < 2; ++n) _Pragma("unroll") for (int k = 0; k < 2; ++k) \
;         acc[ai][bj][m][n] = __builtin_amdgcn_mfma_f32_16x16x32_bf16(Bt[n][k], At[m][k], acc[ai][bj][m][n], 0, 0, 0); __builtin_amdgcn_s_setprio(0); } while (0)
; #define PG8_WAIT_V(n) asm volatile("s_waitcnt vmcnt(" #n ")" ::: "memory")
; #define PG8_WAIT_L(n) asm volatile("s_waitcnt lgkmcnt(" #n ")" ::: "memory")
; #define PG8_BAR __builtin_amdgcn_s_barrier()
; template <class Epi, class Sched>
; DI void gemm_phase(LAS unsigned char* lds, const Sched& S, const Epi& E) {
;     ...
;         for (int t = 0; t < nt; t += 2) {
;             const bool last = (t == nt - 2);
;             const char* a1 = cA + (size_t)(t + 1) * kstep;
;             const char* a2 = last ? nA : cA + (size_t)(t + 2) * kstep; const char* b2 = last ? nB : cB + (size_t)(t + 2) * kstep;
;             const char* a3 = a2 + kstep; const char* b3 = b2 + kstep;
;             if constexpr (Epi::HOOK) { if (cur.ks < 0 && (t == 16 || t == 32)) E.hook(acc, cur, t >> 4, wr, wc, fr, fq); }
;             PG8_LDB(B0, 0, 0); PG8_LDB(B1, 0, 1); PG8_SCHED; PG8_LDA(At, 0, 0); PG8_STAGE(PG8_SA(1, 1), a1 + hstepA, voffA);
;             PG8_WAIT_V(8); PG8_WAIT_L(0); PG8_BAR; PG8_MMA(0, 0, At, B0); PG8_MMA(0, 1, At, B1); PG8_BAR; PG8_SCHED;
;             PG8_LDA(At, 0, 1); PG8_STAGE(PG8_SB(0, 0), b2, voffB); PG8_STAGE(PG8_SB(0, 1), b2 + hstepB, voffB); PG8_STAGE(PG8_SA(0, 0), a2, voffA);
;             PG8_WAIT_V(8); PG8_WAIT_L(0); PG8_BAR; PG8_MMA(1, 0, At, B0); PG8_MMA(1, 1, At, B1); PG8_BAR; PG8_SCHED;
.LBB0_1390:
	v_add_u32_e32 v216, 0x10000, v148
	s_add_u32 s50, s48, 0xfff80080
	s_addc_u32 s51, s49, -1
	s_add_i32 s66, 0, 0x10000
	s_cmp_eq_u32 s65, 28
	s_cselect_b32 s53, s45, s51
	s_cselect_b32 s52, s44, s50
	s_cselect_b32 s51, s47, s43
	s_cselect_b32 s50, s46, s39
	s_add_i32 s71, 0, 0x14000
	ds_read_b128 v[144:147], v216
	ds_read_b128 v[152:155], v216 offset:1024
	ds_read_b128 v[156:159], v216 offset:2048
	ds_read_b128 v[160:163], v216 offset:3072
	ds_read_b128 v[164:167], v216 offset:16384
	ds_read_b128 v[168:171], v216 offset:17408
	ds_read_b128 v[172:175], v216 offset:18432
	ds_read_b128 v[176:179], v216 offset:19456
	s_add_i32 m0, s54, 0xc000
	ds_read_b128 v[180:183], v151
	ds_read_b128 v[184:187], v151 offset:1024
	ds_read_b128 v[188:191], v151 offset:2048
	ds_read_b128 v[192:195], v151 offset:3072
	ds_read_b128 v[204:207], v151 offset:4096
	ds_read_b128 v[208:211], v151 offset:5120
	ds_read_b128 v[212:215], v151 offset:6144
	global_load_lds_dwordx4 v142, s[48:49]
	s_add_i32 m0, s54, 0xe000
	ds_read_b128 v[230:233], v151 offset:7168
	global_load_lds_dwordx4 v140, s[48:49]
	s_waitcnt vmcnt(8) lgkmcnt(0)
	s_barrier
	s_setprio 1
	v_mfma_f32_16x16x32_bf16 v[128:131], v[144:147], v[180:183], v[128:131]
	v_mfma_f32_16x16x32_bf16 v[124:127], v[156:159], v[180:183], v[124:127]
	v_mfma_f32_16x16x32_bf16 v[112:115], v[144:147], v[188:191], v[112:115]
	v_mfma_f32_16x16x32_bf16 v[108:111], v[156:159], v[188:191], v[108:111]
	v_mfma_f32_16x16x32_bf16 v[96:99], v[144:147], v[204:207], v[96:99]
	v_mfma_f32_16x16x32_bf16 v[92:95], v[156:159], v[204:207], v[92:95]
	v_mfma_f32_16x16x32_bf16 v[80:83], v[144:147], v[212:215], v[80:83]
	v_mfma_f32_16x16x32_bf16 v[76:79], v[156:159], v[212:215], v[76:79]
	v_mfma_f32_16x16x32_bf16 v[128:131], v[152:155], v[184:187], v[128:131]
	v_mfma_f32_16x16x32_bf16 v[124:127], v[160:163], v[184:187], v[124:127]
	v_mfma_f32_16x16x32_bf16 v[112:115], v[152:155], v[192:195], v[112:115]
	v_mfma_f32_16x16x32_bf16 v[108:111], v[160:163], v[192:195], v[108:111]
	v_mfma_f32_16x16x32_bf16 v[96:99], v[152:155], v[208:211], v[96:99]
	v_mfma_f32_16x16x32_bf16 v[92:95], v[160:163], v[208:211], v[92:95]
	v_mfma_f32_16x16x32_bf16 v[80:83], v[152:155], v[230:233], v[80:83]
	v_mfma_f32_16x16x32_bf16 v[76:79], v[160:163], v[230:233], v[76:79]
	v_mfma_f32_16x16x32_bf16 v[120:123], v[164:167], v[180:183], v[120:123]
	v_mfma_f32_16x16x32_bf16 v[116:119], v[172:175], v[180:183], v[116:119]
	v_mfma_f32_16x16x32_bf16 v[104:107], v[164:167], v[188:191], v[104:107]
	v_mfma_f32_16x16x32_bf16 v[100:103], v[172:175], v[188:191], v[100:103]
	v_mfma_f32_16x16x32_bf16 v[88:91], v[164:167], v[204:207], v[88:91]
	v_mfma_f32_16x16x32_bf16 v[84:87], v[172:175], v[204:207], v[84:87]
	v_mfma_f32_16x16x32_bf16 v[72:75], v[164:167], v[212:215], v[72:75]
	v_mfma_f32_16x16x32_bf16 v[68:71], v[172:175], v[212:215], v[68:71]
	v_mfma_f32_16x16x32_bf16 v[120:123], v[168:171], v[184:187], v[120:123]
	v_mfma_f32_16x16x32_bf16 v[116:119], v[176:179], v[184:187], v[116:119]
	v_mfma_f32_16x16x32_bf16 v[104:107], v[168:171], v[192:195], v[104:107]
	v_mfma_f32_16x16x32_bf16 v[100:103], v[176:179], v[192:195], v[100:103]
	v_mfma_f32_16x16x32_bf16 v[88:91], v[168:171], v[208:211], v[88:91]
	v_mfma_f32_16x16x32_bf16 v[84:87], v[176:179], v[208:211], v[84:87]
	v_mfma_f32_16x16x32_bf16 v[72:75], v[168:171], v[230:233], v[72:75]
	v_mfma_f32_16x16x32_bf16 v[68:71], v[176:179], v[230:233], v[68:71]
	s_setprio 0
	s_barrier
	s_add_i32 s66, s66, s27
	s_mov_b32 m0, s66
	ds_read_b128 v[180:183], v151 offset:16384
	ds_read_b128 v[184:187], v151 offset:17408
	ds_read_b128 v[188:191], v151 offset:18432
	ds_read_b128 v[192:195], v151 offset:19456
	ds_read_b128 v[204:207], v151 offset:20480
	global_load_lds_dwordx4 v2, s[50:51]
	s_add_i32 m0, s66, 0x2000
	s_add_u32 s66, s50, 0x80000
	s_addc_u32 s67, s51, 0
	s_add_i32 s71, s71, s27
	global_load_lds_dwordx4 v136, s[50:51]
	s_mov_b32 m0, s71
	s_add_u32 s86, s52, 0x80
	s_addc_u32 s87, s53, 0
	global_load_lds_dwordx4 v2, s[66:67]
	s_add_i32 m0, s71, 0x2000
	ds_read_b128 v[230:233], v151 offset:23552
	global_load_lds_dwordx4 v136, s[66:67]
	s_mov_b32 m0, s54
	ds_read_b128 v[212:215], v151 offset:22528
	global_load_lds_dwordx4 v132, s[52:53]
	s_mov_b32 m0, s55
	ds_read_b128 v[208:211], v151 offset:21504
	global_load_lds_dwordx4 v134, s[52:53]
	s_waitcnt vmcnt(8) lgkmcnt(0)
	s_barrier
	s_setprio 1
	v_mfma_f32_16x16x32_bf16 v[64:67], v[144:147], v[180:183], v[64:67]
	v_mfma_f32_16x16x32_bf16 v[60:63], v[156:159], v[180:183], v[60:63]
	v_mfma_f32_16x16x32_bf16 v[48:51], v[144:147], v[188:191], v[48:51]
	v_mfma_f32_16x16x32_bf16 v[44:47], v[156:159], v[188:191], v[44:47]
	v_mfma_f32_16x16x32_bf16 v[32:35], v[144:147], v[204:207], v[32:35]
	v_mfma_f32_16x16x32_bf16 v[28:31], v[156:159], v[204:207], v[28:31]
	v_mfma_f32_16x16x32_bf16 v[16:19], v[144:147], v[212:215], v[16:19]
	v_mfma_f32_16x16x32_bf16 v[12:15], v[156:159], v[212:215], v[12:15]
	v_mfma_f32_16x16x32_bf16 v[64:67], v[152:155], v[184:187], v[64:67]
	v_mfma_f32_16x16x32_bf16 v[60:63], v[160:163], v[184:187], v[60:63]
	v_mfma_f32_16x16x32_bf16 v[48:51], v[152:155], v[192:195], v[48:51]
	v_mfma_f32_16x16x32_bf16 v[44:47], v[160:163], v[192:195], v[44:47]
	v_mfma_f32_16x16x32_bf16 v[32:35], v[152:155], v[208:211], v[32:35]
	v_mfma_f32_16x16x32_bf16 v[28:31], v[160:163], v[208:211], v[28:31]
	v_mfma_f32_16x16x32_bf16 v[16:19], v[152:155], v[230:233], v[16:19]
	v_mfma_f32_16x16x32_bf16 v[12:15], v[160:163], v[230:233], v[12:15]
	v_mfma_f32_16x16x32_bf16 v[56:59], v[164:167], v[180:183], v[56:59]
	v_mfma_f32_16x16x32_bf16 v[52:55], v[172:175], v[180:183], v[52:55]
	v_mfma_f32_16x16x32_bf16 v[40:43], v[164:167], v[188:191], v[40:43]
	v_mfma_f32_16x16x32_bf16 v[36:39], v[172:175], v[188:191], v[36:39]
	v_mfma_f32_16x16x32_bf16 v[24:27], v[164:167], v[204:207], v[24:27]
	v_mfma_f32_16x16x32_bf16 v[20:23], v[172:175], v[204:207], v[20:23]
	v_mfma_f32_16x16x32_bf16 v[8:11], v[164:167], v[212:215], v[8:11]
	v_mfma_f32_16x16x32_bf16 v[4:7], v[172:175], v[212:215], v[4:7]
	v_mfma_f32_16x16x32_bf16 v[56:59], v[168:171], v[184:187], v[56:59]
	v_mfma_f32_16x16x32_bf16 v[52:55], v[176:179], v[184:187], v[52:55]
	v_mfma_f32_16x16x32_bf16 v[40:43], v[168:171], v[192:195], v[40:43]
	v_mfma_f32_16x16x32_bf16 v[36:39], v[176:179], v[192:195], v[36:39]
	v_mfma_f32_16x16x32_bf16 v[24:27], v[168:171], v[208:211], v[24:27]
	v_mfma_f32_16x16x32_bf16 v[20:23], v[176:179], v[208:211], v[20:23]
	v_mfma_f32_16x16x32_bf16 v[8:11], v[168:171], v[230:233], v[8:11]
	v_mfma_f32_16x16x32_bf16 v[4:7], v[176:179], v[230:233], v[4:7]
	s_setprio 0
	s_barrier
; #define PG8_STAGE(bufoff, gbase, voff) do { _Pragma("unroll") for (int _i = 0; _i < 2; ++_i) \
;         __builtin_amdgcn_global_load_lds((const unsigned*)((const char*)(gbase) + (voff)[_i]), (LAS unsigned*)(lds + (bufoff) + ldsw + _i * 8192), 16, 0, 0); } while (0)
; #define PG8_LDA(dst, b, h) do { _Pragma("unroll") for (int m = 0; m < 4; ++m) _Pragma("unroll") for (int k = 0; k < 2; ++k) dst[m][k] = *(const LAS bf16x8*)(lds + PG8_SA(b, h) + aoff + m * 2048 + k * 1024); } while (0)
; #define PG8_LDB(dst, b, h) do { _Pragma("unroll") for (int n = 0; n < 2; ++n) _Pragma("unroll") for (int k = 0; k < 2; ++k) dst[n][k] = *(const LAS bf16x8*)(lds + PG8_SB(b, h) + boff + n * 2048 + k * 1024); } while (0)
; #define PG8_MMA(ai, bj, At, Bt) do { __builtin_amdgcn_s_setprio(1); _Pragma("unroll") for (int m = 0; m < 4; ++m) _Pragma("unroll") for (int n = 0; n < 2; ++n) _Pragma("unroll") for (int k = 0; k < 2; ++k) \
;         acc[ai][bj][m][n] = __builtin_amdgcn_mfma_f32_16x16x32_bf16(Bt[n][k], At[m][k], acc[ai][bj][m][n], 0, 0, 0); __builtin_amdgcn_s_setprio(0); } while (0)
; #define PG8_WAIT_V(n) asm volatile("s_waitcnt vmcnt(" #n ")" ::: "memory")
; #define PG8_WAIT_L(n) asm volatile("s_waitcnt lgkmcnt(" #n ")" ::: "memory")
; #define PG8_BAR __builtin_amdgcn_s_barrier()
; #define PG8_SCHED __builtin_amdgcn_sched_barrier(0)
; template <class Epi, class Sched>
; DI void gemm_phase(LAS unsigned char* lds, const Sched& S, const Epi& E) {
;     ...
;             PG8_LDB(B0, 1, 0); PG8_LDB(B1, 1, 1); PG8_SCHED; PG8_LDA(At, 1, 0); PG8_STAGE(PG8_SA(0, 1), a2 + hstepA, voffA);
;             PG8_WAIT_V(8); PG8_WAIT_L(0); PG8_BAR; PG8_MMA(0, 0, At, B0); PG8_MMA(0, 1, At, B1); PG8_BAR; PG8_SCHED;
;             PG8_LDA(At, 1, 1); PG8_STAGE(PG8_SB(1, 0), b3, voffB); PG8_STAGE(PG8_SB(1, 1), b3 + hstepB, voffB); PG8_STAGE(PG8_SA(1, 0), a3, voffA);
;             PG8_WAIT_V(8); PG8_WAIT_L(0); PG8_BAR; PG8_MMA(1, 0, At, B0); PG8_MMA(1, 1, At, B1); PG8_BAR; PG8_SCHED;
;         }
;         if (wr == 0) PG8_BAR;
	s_add_i32 s66, 0, 0x18000
	s_add_i32 s67, 0, 0x1c000
	ds_read_b128 v[144:147], v216 offset:32768
	ds_read_b128 v[152:155], v216 offset:33792
	ds_read_b128 v[156:159], v216 offset:34816
	ds_read_b128 v[160:163], v216 offset:35840
	ds_read_b128 v[164:167], v216 offset:49152
	ds_read_b128 v[168:171], v216 offset:50176
	ds_read_b128 v[172:175], v216 offset:51200
	ds_read_b128 v[176:179], v216 offset:52224
	s_add_u32 s52, s52, 0x80000
	s_addc_u32 s53, s53, 0
	s_mov_b32 m0, s56
	ds_read_b128 v[180:183], v151 offset:32768
	ds_read_b128 v[184:187], v151 offset:33792
	ds_read_b128 v[188:191], v151 offset:34816
	ds_read_b128 v[192:195], v151 offset:35840
	ds_read_b128 v[204:207], v151 offset:36864
	ds_read_b128 v[208:211], v151 offset:37888
	ds_read_b128 v[212:215], v151 offset:38912
	global_load_lds_dwordx4 v132, s[52:53]
	s_mov_b32 m0, s57
	ds_read_b128 v[230:233], v151 offset:39936
	global_load_lds_dwordx4 v134, s[52:53]
	s_waitcnt vmcnt(8) lgkmcnt(0)
	s_barrier
	s_setprio 1
	v_mfma_f32_16x16x32_bf16 v[128:131], v[144:147], v[180:183], v[128:131]
	v_mfma_f32_16x16x32_bf16 v[124:127], v[156:159], v[180:183], v[124:127]
	v_mfma_f32_16x16x32_bf16 v[112:115], v[144:147], v[188:191], v[112:115]
	v_mfma_f32_16x16x32_bf16 v[108:111], v[156:159], v[188:191], v[108:111]
	v_mfma_f32_16x16x32_bf16 v[96:99], v[144:147], v[204:207], v[96:99]
	v_mfma_f32_16x16x32_bf16 v[92:95], v[156:159], v[204:207], v[92:95]
	v_mfma_f32_16x16x32_bf16 v[80:83], v[144:147], v[212:215], v[80:83]
	v_mfma_f32_16x16x32_bf16 v[76:79], v[156:159], v[212:215], v[76:79]
	v_mfma_f32_16x16x32_bf16 v[128:131], v[152:155], v[184:187], v[128:131]
	v_mfma_f32_16x16x32_bf16 v[124:127], v[160:163], v[184:187], v[124:127]
	v_mfma_f32_16x16x32_bf16 v[112:115], v[152:155], v[192:195], v[112:115]
	v_mfma_f32_16x16x32_bf16 v[108:111], v[160:163], v[192:195], v[108:111]
	v_mfma_f32_16x16x32_bf16 v[96:99], v[152:155], v[208:211], v[96:99]
	v_mfma_f32_16x16x32_bf16 v[92:95], v[160:163], v[208:211], v[92:95]
	v_mfma_f32_16x16x32_bf16 v[80:83], v[152:155], v[230:233], v[80:83]
	v_mfma_f32_16x16x32_bf16 v[76:79], v[160:163], v[230:233], v[76:79]
	v_mfma_f32_16x16x32_bf16 v[120:123], v[164:167], v[180:183], v[120:123]
	v_mfma_f32_16x16x32_bf16 v[116:119], v[172:175], v[180:183], v[116:119]
	v_mfma_f32_16x16x32_bf16 v[104:107], v[164:167], v[188:191], v[104:107]
	v_mfma_f32_16x16x32_bf16 v[100:103], v[172:175], v[188:191], v[100:103]
	v_mfma_f32_16x16x32_bf16 v[88:91], v[164:167], v[204:207], v[88:91]
	v_mfma_f32_16x16x32_bf16 v[84:87], v[172:175], v[204:207], v[84:87]
	v_mfma_f32_16x16x32_bf16 v[72:75], v[164:167], v[212:215], v[72:75]
	v_mfma_f32_16x16x32_bf16 v[68:71], v[172:175], v[212:215], v[68:71]
	v_mfma_f32_16x16x32_bf16 v[120:123], v[168:171], v[184:187], v[120:123]
	v_mfma_f32_16x16x32_bf16 v[116:119], v[176:179], v[184:187], v[116:119]
	v_mfma_f32_16x16x32_bf16 v[104:107], v[168:171], v[192:195], v[104:107]
	v_mfma_f32_16x16x32_bf16 v[100:103], v[176:179], v[192:195], v[100:103]
	v_mfma_f32_16x16x32_bf16 v[88:91], v[168:171], v[208:211], v[88:91]
	v_mfma_f32_16x16x32_bf16 v[84:87], v[176:179], v[208:211], v[84:87]
	v_mfma_f32_16x16x32_bf16 v[72:75], v[168:171], v[230:233], v[72:75]
	v_mfma_f32_16x16x32_bf16 v[68:71], v[176:179], v[230:233], v[68:71]
	s_setprio 0
	s_barrier
	s_add_i32 s52, s66, s27
	s_add_u32 s50, s50, 0x80
	s_addc_u32 s51, s51, 0
	s_mov_b32 m0, s52
	ds_read_b128 v[180:183], v151 offset:49152
	ds_read_b128 v[184:187], v151 offset:50176
	ds_read_b128 v[188:191], v151 offset:51200
	ds_read_b128 v[192:195], v151 offset:52224
	global_load_lds_dwordx4 v2, s[50:51]
	s_add_i32 m0, s52, 0x2000
	s_add_i32 s52, s67, s27
	global_load_lds_dwordx4 v136, s[50:51]
	s_add_u32 s50, s50, 0x80000
	s_addc_u32 s51, s51, 0
	s_mov_b32 m0, s52
	ds_read_b128 v[230:233], v151 offset:56320
	global_load_lds_dwordx4 v2, s[50:51]
	s_add_i32 m0, s52, 0x2000
	ds_read_b128 v[212:215], v151 offset:55296
	global_load_lds_dwordx4 v136, s[50:51]
	s_mov_b32 m0, s58
	ds_read_b128 v[208:211], v151 offset:54272
	global_load_lds_dwordx4 v132, s[86:87]
	s_mov_b32 m0, s59
	ds_read_b128 v[204:207], v151 offset:53248
	global_load_lds_dwordx4 v134, s[86:87]
	s_waitcnt vmcnt(8) lgkmcnt(0)
	s_barrier
	s_setprio 1
	v_mfma_f32_16x16x32_bf16 v[64:67], v[144:147], v[180:183], v[64:67]
	v_mfma_f32_16x16x32_bf16 v[60:63], v[156:159], v[180:183], v[60:63]
	v_mfma_f32_16x16x32_bf16 v[48:51], v[144:147], v[188:191], v[48:51]
	v_mfma_f32_16x16x32_bf16 v[44:47], v[156:159], v[188:191], v[44:47]
	v_mfma_f32_16x16x32_bf16 v[32:35], v[144:147], v[204:207], v[32:35]
	v_mfma_f32_16x16x32_bf16 v[28:31], v[156:159], v[204:207], v[28:31]
	v_mfma_f32_16x16x32_bf16 v[16:19], v[144:147], v[212:215], v[16:19]
	v_mfma_f32_16x16x32_bf16 v[12:15], v[156:159], v[212:215], v[12:15]
	v_mfma_f32_16x16x32_bf16 v[64:67], v[152:155], v[184:187], v[64:67]
	v_mfma_f32_16x16x32_bf16 v[60:63], v[160:163], v[184:187], v[60:63]
	v_mfma_f32_16x16x32_bf16 v[48:51], v[152:155], v[192:195], v[48:51]
	v_mfma_f32_16x16x32_bf16 v[44:47], v[160:163], v[192:195], v[44:47]
	v_mfma_f32_16x16x32_bf16 v[32:35], v[152:155], v[208:211], v[32:35]
	v_mfma_f32_16x16x32_bf16 v[28:31], v[160:163], v[208:211], v[28:31]
	v_mfma_f32_16x16x32_bf16 v[16:19], v[152:155], v[230:233], v[16:19]
	v_mfma_f32_16x16x32_bf16 v[12:15], v[160:163], v[230:233], v[12:15]
	v_mfma_f32_16x16x32_bf16 v[56:59], v[164:167], v[180:183], v[56:59]
	v_mfma_f32_16x16x32_bf16 v[52:55], v[172:175], v[180:183], v[52:55]
	v_mfma_f32_16x16x32_bf16 v[40:43], v[164:167], v[188:191], v[40:43]
	v_mfma_f32_16x16x32_bf16 v[36:39], v[172:175], v[188:191], v[36:39]
	v_mfma_f32_16x16x32_bf16 v[24:27], v[164:167], v[204:207], v[24:27]
	v_mfma_f32_16x16x32_bf16 v[20:23], v[172:175], v[204:207], v[20:23]
	v_mfma_f32_16x16x32_bf16 v[8:11], v[164:167], v[212:215], v[8:11]
	v_mfma_f32_16x16x32_bf16 v[4:7], v[172:175], v[212:215], v[4:7]
	v_mfma_f32_16x16x32_bf16 v[56:59], v[168:171], v[184:187], v[56:59]
	v_mfma_f32_16x16x32_bf16 v[52:55], v[176:179], v[184:187], v[52:55]
	v_mfma_f32_16x16x32_bf16 v[40:43], v[168:171], v[192:195], v[40:43]
	v_mfma_f32_16x16x32_bf16 v[36:39], v[176:179], v[192:195], v[36:39]
	v_mfma_f32_16x16x32_bf16 v[24:27], v[168:171], v[208:211], v[24:27]
	v_mfma_f32_16x16x32_bf16 v[20:23], v[176:179], v[208:211], v[20:23]
	v_mfma_f32_16x16x32_bf16 v[8:11], v[168:171], v[230:233], v[8:11]
	v_mfma_f32_16x16x32_bf16 v[4:7], v[176:179], v[230:233], v[4:7]
	s_setprio 0
	s_barrier
	s_add_i32 s65, s65, 2
	s_add_u32 s39, s39, 0x100
	s_addc_u32 s43, s43, 0
	s_add_u32 s48, s48, 0x100
	s_addc_u32 s49, s49, 0
	s_cmp_gt_u32 s65, 29
	s_cbranch_scc0 .LBB0_1390
	s_and_b64 vcc, exec, s[34:35]
	s_cbranch_vccz .LBB0_1393
	s_barrier

; #define PG8_STAGE(bufoff, gbase, voff) do { _Pragma("unroll") for (int _i = 0; _i < 2; ++_i) \
;         __builtin_amdgcn_global_load_lds((const unsigned*)((const char*)(gbase) + (voff)[_i]), (LAS unsigned*)(lds + (bufoff) + ldsw + _i * 8192), 16, 0, 0); } while (0)
; #define PG8_LDA(dst, b, h) do { _Pragma("unroll") for (int m = 0; m < 4; ++m) _Pragma("unroll") for (int k = 0; k < 2; ++k) dst[m][k] = *(const LAS bf16x8*)(lds + PG8_SA(b, h) + aoff + m * 2048 + k * 1024); } while (0)
; #define PG8_LDB(dst, b, h) do { _Pragma("unroll") for (int n = 0; n < 2; ++n) _Pragma("unroll") for (int k = 0; k < 2; ++k) dst[n][k] = *(const LAS bf16x8*)(lds + PG8_SB(b, h) + boff + n * 2048 + k * 1024); } while (0)
; #define PG8_MMA(ai, bj, At, Bt) do { __builtin_amdgcn_s_setprio(1); _Pragma("unroll") for (int m = 0; m < 4; ++m) _Pragma("unroll") for (int n = 0; n < 2; ++n) _Pragma("unroll") for (int k = 0; k < 2; ++k) \
;         acc[ai][bj][m][n] = __builtin_amdgcn_mfma_f32_16x16x32_bf16(Bt[n][k], At[m][k], acc[ai][bj][m][n], 0, 0, 0); __builtin_amdgcn_s_setprio(0); } while (0)
; #define PG8_WAIT_V(n) asm volatile("s_waitcnt vmcnt(" #n ")" ::: "memory")
; #define PG8_WAIT_L(n) asm volatile("s_waitcnt lgkmcnt(" #n ")" ::: "memory")
; #define PG8_BAR __builtin_amdgcn_s_barrier()
; template <class Epi, class Sched>
; DI void gemm_phase(LAS unsigned char* lds, const Sched& S, const Epi& E) {
;     ...
;         for (int t = 0; t < nt; t += 2) {
;             const bool last = (t == nt - 2);
;             const char* a1 = cA + (size_t)(t + 1) * kstep;
;             const char* a2 = last ? nA : cA + (size_t)(t + 2) * kstep; const char* b2 = last ? nB : cB + (size_t)(t + 2) * kstep;
;             const char* a3 = a2 + kstep; const char* b3 = b2 + kstep;
;             if constexpr (Epi::HOOK) { if (cur.ks < 0 && (t == 16 || t == 32)) E.hook(acc, cur, t >> 4, wr, wc, fr, fq); }
;             PG8_LDB(B0, 0, 0); PG8_LDB(B1, 0, 1); PG8_SCHED; PG8_LDA(At, 0, 0); PG8_STAGE(PG8_SA(1, 1), a1 + hstepA, voffA);
;             PG8_WAIT_V(8); PG8_WAIT_L(0); PG8_BAR; PG8_MMA(0, 0, At, B0); PG8_MMA(0, 1, At, B1); PG8_BAR; PG8_SCHED;
;             PG8_LDA(At, 0, 1); PG8_STAGE(PG8_SB(0, 0), b2, voffB); PG8_STAGE(PG8_SB(0, 1), b2 + hstepB, voffB); PG8_STAGE(PG8_SA(0, 0), a2, voffA);
;             PG8_WAIT_V(8); PG8_WAIT_L(0); PG8_BAR; PG8_MMA(1, 0, At, B0); PG8_MMA(1, 1, At, B1); PG8_BAR; PG8_SCHED;
.LBB0_1470:
	v_add_u32_e32 v214, 0x10000, v197
	s_add_i32 s82, s52, 2
	s_add_u32 s53, s42, 0xffe00080
	s_addc_u32 s54, s43, -1
	s_add_i32 s83, 0, 0x10000
	s_cmp_eq_u32 s79, s52
	s_cselect_b32 s55, s56, s54
	s_cselect_b32 s54, s57, s53
	s_cselect_b32 s53, s58, s81
	s_cselect_b32 s52, s59, s80
	s_add_i32 s85, 0, 0x14000
	ds_read_b128 v[84:87], v214
	ds_read_b128 v[88:91], v214 offset:1024
	ds_read_b128 v[104:107], v214 offset:2048
	ds_read_b128 v[112:115], v214 offset:3072
	ds_read_b128 v[124:127], v214 offset:16384
	ds_read_b128 v[136:139], v214 offset:17408
	ds_read_b128 v[148:151], v214 offset:18432
	ds_read_b128 v[160:163], v214 offset:19456
	s_add_i32 m0, s61, 0xc000
	ds_read_b128 v[164:167], v231
	ds_read_b128 v[168:171], v231 offset:1024
	ds_read_b128 v[172:175], v231 offset:2048
	ds_read_b128 v[176:179], v231 offset:3072
	ds_read_b128 v[180:183], v231 offset:4096
	ds_read_b128 v[184:187], v231 offset:5120
	ds_read_b128 v[188:191], v231 offset:6144
	global_load_lds_dwordx4 v212, s[42:43]
	s_add_i32 m0, s61, 0xe000
	ds_read_b128 v[192:195], v231 offset:7168
	global_load_lds_dwordx4 v210, s[42:43]
	s_waitcnt vmcnt(8) lgkmcnt(0)
	s_barrier
	s_setprio 1
	v_mfma_f32_16x16x32_bf16 v[156:159], v[84:87], v[164:167], v[156:159]
	v_mfma_f32_16x16x32_bf16 v[152:155], v[104:107], v[164:167], v[152:155]
	v_mfma_f32_16x16x32_bf16 v[132:135], v[84:87], v[172:175], v[132:135]
	v_mfma_f32_16x16x32_bf16 v[128:131], v[104:107], v[172:175], v[128:131]
	v_mfma_f32_16x16x32_bf16 v[108:111], v[84:87], v[180:183], v[108:111]
	v_mfma_f32_16x16x32_bf16 v[100:103], v[104:107], v[180:183], v[100:103]
	v_mfma_f32_16x16x32_bf16 v[80:83], v[84:87], v[188:191], v[80:83]
	v_mfma_f32_16x16x32_bf16 v[76:79], v[104:107], v[188:191], v[76:79]
	v_mfma_f32_16x16x32_bf16 v[156:159], v[88:91], v[168:171], v[156:159]
	v_mfma_f32_16x16x32_bf16 v[152:155], v[112:115], v[168:171], v[152:155]
	v_mfma_f32_16x16x32_bf16 v[132:135], v[88:91], v[176:179], v[132:135]
	v_mfma_f32_16x16x32_bf16 v[128:131], v[112:115], v[176:179], v[128:131]
	v_mfma_f32_16x16x32_bf16 v[108:111], v[88:91], v[184:187], v[108:111]
	v_mfma_f32_16x16x32_bf16 v[100:103], v[112:115], v[184:187], v[100:103]
	v_mfma_f32_16x16x32_bf16 v[80:83], v[88:91], v[192:195], v[80:83]
	v_mfma_f32_16x16x32_bf16 v[76:79], v[112:115], v[192:195], v[76:79]
	v_mfma_f32_16x16x32_bf16 v[144:147], v[124:127], v[164:167], v[144:147]
	v_mfma_f32_16x16x32_bf16 v[140:143], v[148:151], v[164:167], v[140:143]
	v_mfma_f32_16x16x32_bf16 v[120:123], v[124:127], v[172:175], v[120:123]
	v_mfma_f32_16x16x32_bf16 v[116:119], v[148:151], v[172:175], v[116:119]
	v_mfma_f32_16x16x32_bf16 v[96:99], v[124:127], v[180:183], v[96:99]
	v_mfma_f32_16x16x32_bf16 v[92:95], v[148:151], v[180:183], v[92:95]
	v_mfma_f32_16x16x32_bf16 v[72:75], v[124:127], v[188:191], v[72:75]
	v_mfma_f32_16x16x32_bf16 v[68:71], v[148:151], v[188:191], v[68:71]
	v_mfma_f32_16x16x32_bf16 v[144:147], v[136:139], v[168:171], v[144:147]
	v_mfma_f32_16x16x32_bf16 v[140:143], v[160:163], v[168:171], v[140:143]
	v_mfma_f32_16x16x32_bf16 v[120:123], v[136:139], v[176:179], v[120:123]
	v_mfma_f32_16x16x32_bf16 v[116:119], v[160:163], v[176:179], v[116:119]
	v_mfma_f32_16x16x32_bf16 v[96:99], v[136:139], v[184:187], v[96:99]
	v_mfma_f32_16x16x32_bf16 v[92:95], v[160:163], v[184:187], v[92:95]
	v_mfma_f32_16x16x32_bf16 v[72:75], v[136:139], v[192:195], v[72:75]
	v_mfma_f32_16x16x32_bf16 v[68:71], v[160:163], v[192:195], v[68:71]
	s_setprio 0
	s_barrier
	s_add_i32 s83, s83, s60
	s_mov_b32 m0, s83
	ds_read_b128 v[164:167], v231 offset:16384
	ds_read_b128 v[168:171], v231 offset:17408
	ds_read_b128 v[172:175], v231 offset:18432
	ds_read_b128 v[176:179], v231 offset:19456
	global_load_lds_dwordx4 v2, s[52:53]
	s_add_i32 m0, s83, 0x2000
	s_add_u32 s86, s52, 0x200000
	s_addc_u32 s87, s53, 0
	s_add_i32 s83, s85, s60
	global_load_lds_dwordx4 v208, s[52:53]
	s_mov_b32 m0, s83
	ds_read_b128 v[192:195], v231 offset:23552
	global_load_lds_dwordx4 v2, s[86:87]
	s_add_i32 m0, s83, 0x2000
	ds_read_b128 v[188:191], v231 offset:22528
	global_load_lds_dwordx4 v208, s[86:87]
	s_add_u32 s98, s54, 0x80
	s_addc_u32 s99, s55, 0
	s_mov_b32 m0, s61
	ds_read_b128 v[184:187], v231 offset:21504
	global_load_lds_dwordx4 v204, s[54:55]
	s_mov_b32 m0, s62
	ds_read_b128 v[180:183], v231 offset:20480
	global_load_lds_dwordx4 v206, s[54:55]
	s_waitcnt vmcnt(8) lgkmcnt(0)
	s_barrier
	s_setprio 1
	v_mfma_f32_16x16x32_bf16 v[64:67], v[84:87], v[164:167], v[64:67]
	v_mfma_f32_16x16x32_bf16 v[60:63], v[104:107], v[164:167], v[60:63]
	v_mfma_f32_16x16x32_bf16 v[48:51], v[84:87], v[172:175], v[48:51]
	v_mfma_f32_16x16x32_bf16 v[44:47], v[104:107], v[172:175], v[44:47]
	v_mfma_f32_16x16x32_bf16 v[32:35], v[84:87], v[180:183], v[32:35]
	v_mfma_f32_16x16x32_bf16 v[28:31], v[104:107], v[180:183], v[28:31]
	v_mfma_f32_16x16x32_bf16 v[16:19], v[84:87], v[188:191], v[16:19]
	v_mfma_f32_16x16x32_bf16 v[12:15], v[104:107], v[188:191], v[12:15]
	v_mfma_f32_16x16x32_bf16 v[64:67], v[88:91], v[168:171], v[64:67]
	v_mfma_f32_16x16x32_bf16 v[60:63], v[112:115], v[168:171], v[60:63]
	v_mfma_f32_16x16x32_bf16 v[48:51], v[88:91], v[176:179], v[48:51]
	v_mfma_f32_16x16x32_bf16 v[44:47], v[112:115], v[176:179], v[44:47]
	v_mfma_f32_16x16x32_bf16 v[32:35], v[88:91], v[184:187], v[32:35]
	v_mfma_f32_16x16x32_bf16 v[28:31], v[112:115], v[184:187], v[28:31]
	v_mfma_f32_16x16x32_bf16 v[16:19], v[88:91], v[192:195], v[16:19]
	v_mfma_f32_16x16x32_bf16 v[12:15], v[112:115], v[192:195], v[12:15]
	v_mfma_f32_16x16x32_bf16 v[56:59], v[124:127], v[164:167], v[56:59]
	v_mfma_f32_16x16x32_bf16 v[52:55], v[148:151], v[164:167], v[52:55]
	v_mfma_f32_16x16x32_bf16 v[40:43], v[124:127], v[172:175], v[40:43]
	v_mfma_f32_16x16x32_bf16 v[36:39], v[148:151], v[172:175], v[36:39]
	v_mfma_f32_16x16x32_bf16 v[24:27], v[124:127], v[180:183], v[24:27]
	v_mfma_f32_16x16x32_bf16 v[20:23], v[148:151], v[180:183], v[20:23]
	v_mfma_f32_16x16x32_bf16 v[8:11], v[124:127], v[188:191], v[8:11]
	v_mfma_f32_16x16x32_bf16 v[4:7], v[148:151], v[188:191], v[4:7]
	v_mfma_f32_16x16x32_bf16 v[56:59], v[136:139], v[168:171], v[56:59]
	v_mfma_f32_16x16x32_bf16 v[52:55], v[160:163], v[168:171], v[52:55]
	v_mfma_f32_16x16x32_bf16 v[40:43], v[136:139], v[176:179], v[40:43]
	v_mfma_f32_16x16x32_bf16 v[36:39], v[160:163], v[176:179], v[36:39]
	v_mfma_f32_16x16x32_bf16 v[24:27], v[136:139], v[184:187], v[24:27]
	v_mfma_f32_16x16x32_bf16 v[20:23], v[160:163], v[184:187], v[20:23]
	v_mfma_f32_16x16x32_bf16 v[8:11], v[136:139], v[192:195], v[8:11]
	v_mfma_f32_16x16x32_bf16 v[4:7], v[160:163], v[192:195], v[4:7]
	s_setprio 0
	s_barrier
; #define PG8_STAGE(bufoff, gbase, voff) do { _Pragma("unroll") for (int _i = 0; _i < 2; ++_i) \
;         __builtin_amdgcn_global_load_lds((const unsigned*)((const char*)(gbase) + (voff)[_i]), (LAS unsigned*)(lds + (bufoff) + ldsw + _i * 8192), 16, 0, 0); } while (0)
; #define PG8_LDA(dst, b, h) do { _Pragma("unroll") for (int m = 0; m < 4; ++m) _Pragma("unroll") for (int k = 0; k < 2; ++k) dst[m][k] = *(const LAS bf16x8*)(lds + PG8_SA(b, h) + aoff + m * 2048 + k * 1024); } while (0)
; #define PG8_LDB(dst, b, h) do { _Pragma("unroll") for (int n = 0; n < 2; ++n) _Pragma("unroll") for (int k = 0; k < 2; ++k) dst[n][k] = *(const LAS bf16x8*)(lds + PG8_SB(b, h) + boff + n * 2048 + k * 1024); } while (0)
; #define PG8_MMA(ai, bj, At, Bt) do { __builtin_amdgcn_s_setprio(1); _Pragma("unroll") for (int m = 0; m < 4; ++m) _Pragma("unroll") for (int n = 0; n < 2; ++n) _Pragma("unroll") for (int k = 0; k < 2; ++k) \
;         acc[ai][bj][m][n] = __builtin_amdgcn_mfma_f32_16x16x32_bf16(Bt[n][k], At[m][k], acc[ai][bj][m][n], 0, 0, 0); __builtin_amdgcn_s_setprio(0); } while (0)
; #define PG8_WAIT_V(n) asm volatile("s_waitcnt vmcnt(" #n ")" ::: "memory")
; #define PG8_WAIT_L(n) asm volatile("s_waitcnt lgkmcnt(" #n ")" ::: "memory")
; #define PG8_BAR __builtin_amdgcn_s_barrier()
; #define PG8_SCHED __builtin_amdgcn_sched_barrier(0)
; template <class Epi, class Sched>
; DI void gemm_phase(LAS unsigned char* lds, const Sched& S, const Epi& E) {
;     ...
;             PG8_LDB(B0, 1, 0); PG8_LDB(B1, 1, 1); PG8_SCHED; PG8_LDA(At, 1, 0); PG8_STAGE(PG8_SA(0, 1), a2 + hstepA, voffA);
;             PG8_WAIT_V(8); PG8_WAIT_L(0); PG8_BAR; PG8_MMA(0, 0, At, B0); PG8_MMA(0, 1, At, B1); PG8_BAR; PG8_SCHED;
;             PG8_LDA(At, 1, 1); PG8_STAGE(PG8_SB(1, 0), b3, voffB); PG8_STAGE(PG8_SB(1, 1), b3 + hstepB, voffB); PG8_STAGE(PG8_SA(1, 0), a3, voffA);
;             PG8_WAIT_V(8); PG8_WAIT_L(0); PG8_BAR; PG8_MMA(1, 0, At, B0); PG8_MMA(1, 1, At, B1); PG8_BAR; PG8_SCHED;
;         }
;         if (wr == 0) PG8_BAR;
	s_add_i32 s83, 0, 0x18000
	s_add_i32 s85, 0, 0x1c000
	ds_read_b128 v[84:87], v214 offset:32768
	ds_read_b128 v[88:91], v214 offset:33792
	ds_read_b128 v[104:107], v214 offset:34816
	ds_read_b128 v[112:115], v214 offset:35840
	ds_read_b128 v[124:127], v214 offset:49152
	ds_read_b128 v[136:139], v214 offset:50176
	ds_read_b128 v[148:151], v214 offset:51200
	ds_read_b128 v[160:163], v214 offset:52224
	s_add_u32 s54, s54, 0x200000
	s_addc_u32 s55, s55, 0
	s_mov_b32 m0, s63
	ds_read_b128 v[164:167], v231 offset:32768
	ds_read_b128 v[168:171], v231 offset:33792
	ds_read_b128 v[172:175], v231 offset:34816
	ds_read_b128 v[176:179], v231 offset:35840
	ds_read_b128 v[180:183], v231 offset:36864
	ds_read_b128 v[184:187], v231 offset:37888
	ds_read_b128 v[188:191], v231 offset:38912
	global_load_lds_dwordx4 v204, s[54:55]
	s_mov_b32 m0, s64
	ds_read_b128 v[192:195], v231 offset:39936
	global_load_lds_dwordx4 v206, s[54:55]
	s_waitcnt vmcnt(8) lgkmcnt(0)
	s_barrier
	s_setprio 1
	v_mfma_f32_16x16x32_bf16 v[156:159], v[84:87], v[164:167], v[156:159]
	v_mfma_f32_16x16x32_bf16 v[152:155], v[104:107], v[164:167], v[152:155]
	v_mfma_f32_16x16x32_bf16 v[132:135], v[84:87], v[172:175], v[132:135]
	v_mfma_f32_16x16x32_bf16 v[128:131], v[104:107], v[172:175], v[128:131]
	v_mfma_f32_16x16x32_bf16 v[108:111], v[84:87], v[180:183], v[108:111]
	v_mfma_f32_16x16x32_bf16 v[100:103], v[104:107], v[180:183], v[100:103]
	v_mfma_f32_16x16x32_bf16 v[80:83], v[84:87], v[188:191], v[80:83]
	v_mfma_f32_16x16x32_bf16 v[76:79], v[104:107], v[188:191], v[76:79]
	v_mfma_f32_16x16x32_bf16 v[156:159], v[88:91], v[168:171], v[156:159]
	v_mfma_f32_16x16x32_bf16 v[152:155], v[112:115], v[168:171], v[152:155]
	v_mfma_f32_16x16x32_bf16 v[132:135], v[88:91], v[176:179], v[132:135]
	v_mfma_f32_16x16x32_bf16 v[128:131], v[112:115], v[176:179], v[128:131]
	v_mfma_f32_16x16x32_bf16 v[108:111], v[88:91], v[184:187], v[108:111]
	v_mfma_f32_16x16x32_bf16 v[100:103], v[112:115], v[184:187], v[100:103]
	v_mfma_f32_16x16x32_bf16 v[80:83], v[88:91], v[192:195], v[80:83]
	v_mfma_f32_16x16x32_bf16 v[76:79], v[112:115], v[192:195], v[76:79]
	v_mfma_f32_16x16x32_bf16 v[144:147], v[124:127], v[164:167], v[144:147]
	v_mfma_f32_16x16x32_bf16 v[140:143], v[148:151], v[164:167], v[140:143]
	v_mfma_f32_16x16x32_bf16 v[120:123], v[124:127], v[172:175], v[120:123]
	v_mfma_f32_16x16x32_bf16 v[116:119], v[148:151], v[172:175], v[116:119]
	v_mfma_f32_16x16x32_bf16 v[96:99], v[124:127], v[180:183], v[96:99]
	v_mfma_f32_16x16x32_bf16 v[92:95], v[148:151], v[180:183], v[92:95]
	v_mfma_f32_16x16x32_bf16 v[72:75], v[124:127], v[188:191], v[72:75]
	v_mfma_f32_16x16x32_bf16 v[68:71], v[148:151], v[188:191], v[68:71]
	v_mfma_f32_16x16x32_bf16 v[144:147], v[136:139], v[168:171], v[144:147]
	v_mfma_f32_16x16x32_bf16 v[140:143], v[160:163], v[168:171], v[140:143]
	v_mfma_f32_16x16x32_bf16 v[120:123], v[136:139], v[176:179], v[120:123]
	v_mfma_f32_16x16x32_bf16 v[116:119], v[160:163], v[176:179], v[116:119]
	v_mfma_f32_16x16x32_bf16 v[96:99], v[136:139], v[184:187], v[96:99]
	v_mfma_f32_16x16x32_bf16 v[92:95], v[160:163], v[184:187], v[92:95]
	v_mfma_f32_16x16x32_bf16 v[72:75], v[136:139], v[192:195], v[72:75]
	v_mfma_f32_16x16x32_bf16 v[68:71], v[160:163], v[192:195], v[68:71]
	s_setprio 0
	s_barrier
	s_add_i32 s54, s83, s60
	s_add_u32 s52, s52, 0x80
	s_addc_u32 s53, s53, 0
	s_mov_b32 m0, s54
	ds_read_b128 v[164:167], v231 offset:49152
	ds_read_b128 v[168:171], v231 offset:50176
	ds_read_b128 v[172:175], v231 offset:51200
	ds_read_b128 v[176:179], v231 offset:52224
	global_load_lds_dwordx4 v2, s[52:53]
	s_add_i32 m0, s54, 0x2000
	s_add_i32 s54, s85, s60
	global_load_lds_dwordx4 v208, s[52:53]
	s_add_u32 s52, s52, 0x200000
	s_addc_u32 s53, s53, 0
	s_mov_b32 m0, s54
	ds_read_b128 v[192:195], v231 offset:56320
	global_load_lds_dwordx4 v2, s[52:53]
	s_add_i32 m0, s54, 0x2000
	ds_read_b128 v[188:191], v231 offset:55296
	global_load_lds_dwordx4 v208, s[52:53]
	s_mov_b32 m0, s71
	ds_read_b128 v[184:187], v231 offset:54272
	global_load_lds_dwordx4 v204, s[98:99]
	s_mov_b32 m0, s72
	ds_read_b128 v[180:183], v231 offset:53248
	global_load_lds_dwordx4 v206, s[98:99]
	s_waitcnt vmcnt(8) lgkmcnt(0)
	s_barrier
	s_setprio 1
	v_mfma_f32_16x16x32_bf16 v[64:67], v[84:87], v[164:167], v[64:67]
	v_mfma_f32_16x16x32_bf16 v[60:63], v[104:107], v[164:167], v[60:63]
	v_mfma_f32_16x16x32_bf16 v[48:51], v[84:87], v[172:175], v[48:51]
	v_mfma_f32_16x16x32_bf16 v[44:47], v[104:107], v[172:175], v[44:47]
	v_mfma_f32_16x16x32_bf16 v[32:35], v[84:87], v[180:183], v[32:35]
	v_mfma_f32_16x16x32_bf16 v[28:31], v[104:107], v[180:183], v[28:31]
	v_mfma_f32_16x16x32_bf16 v[16:19], v[84:87], v[188:191], v[16:19]
	v_mfma_f32_16x16x32_bf16 v[12:15], v[104:107], v[188:191], v[12:15]
	v_mfma_f32_16x16x32_bf16 v[64:67], v[88:91], v[168:171], v[64:67]
	v_mfma_f32_16x16x32_bf16 v[60:63], v[112:115], v[168:171], v[60:63]
	v_mfma_f32_16x16x32_bf16 v[48:51], v[88:91], v[176:179], v[48:51]
	v_mfma_f32_16x16x32_bf16 v[44:47], v[112:115], v[176:179], v[44:47]
	v_mfma_f32_16x16x32_bf16 v[32:35], v[88:91], v[184:187], v[32:35]
	v_mfma_f32_16x16x32_bf16 v[28:31], v[112:115], v[184:187], v[28:31]
	v_mfma_f32_16x16x32_bf16 v[16:19], v[88:91], v[192:195], v[16:19]
	v_mfma_f32_16x16x32_bf16 v[12:15], v[112:115], v[192:195], v[12:15]
	v_mfma_f32_16x16x32_bf16 v[56:59], v[124:127], v[164:167], v[56:59]
	v_mfma_f32_16x16x32_bf16 v[52:55], v[148:151], v[164:167], v[52:55]
	v_mfma_f32_16x16x32_bf16 v[40:43], v[124:127], v[172:175], v[40:43]
	v_mfma_f32_16x16x32_bf16 v[36:39], v[148:151], v[172:175], v[36:39]
	v_mfma_f32_16x16x32_bf16 v[24:27], v[124:127], v[180:183], v[24:27]
	v_mfma_f32_16x16x32_bf16 v[20:23], v[148:151], v[180:183], v[20:23]
	v_mfma_f32_16x16x32_bf16 v[8:11], v[124:127], v[188:191], v[8:11]
	v_mfma_f32_16x16x32_bf16 v[4:7], v[148:151], v[188:191], v[4:7]
	v_mfma_f32_16x16x32_bf16 v[56:59], v[136:139], v[168:171], v[56:59]
	v_mfma_f32_16x16x32_bf16 v[52:55], v[160:163], v[168:171], v[52:55]
	v_mfma_f32_16x16x32_bf16 v[40:43], v[136:139], v[176:179], v[40:43]
	v_mfma_f32_16x16x32_bf16 v[36:39], v[160:163], v[176:179], v[36:39]
	v_mfma_f32_16x16x32_bf16 v[24:27], v[136:139], v[184:187], v[24:27]
	v_mfma_f32_16x16x32_bf16 v[20:23], v[160:163], v[184:187], v[20:23]
	v_mfma_f32_16x16x32_bf16 v[8:11], v[136:139], v[192:195], v[8:11]
	v_mfma_f32_16x16x32_bf16 v[4:7], v[160:163], v[192:195], v[4:7]
	s_setprio 0
	s_barrier
	s_add_u32 s80, s80, 0x100
	s_addc_u32 s81, s81, 0
	s_add_u32 s42, s42, 0x100
	s_addc_u32 s43, s43, 0
	s_cmp_ge_i32 s82, s75
	s_mov_b32 s52, s82
	s_cbranch_scc0 .LBB0_1470
	s_and_b64 vcc, exec, s[38:39]
	s_cbranch_vccz .LBB0_1473
	s_barrier
